# planar Z workspace layout (contiguous fourier pre-activation stores) on top of residual-in-K-loop
# speedup vs baseline: 1.5078x; 1.0102x over previous
; __device__ __forceinline__ float silu_f(float z) { return z * __builtin_amdgcn_rcpf(1.0f + __builtin_amdgcn_exp2f(-LOG2E * z)); }
;     __device__ __forceinline__ void operator()(const f32x4 (&acc)[2][2][4][2], const pg8::Unit& u, int ui, LAS unsigned char* lds, int wr, int wc, int fr_, int fq_) const {
;     ...
;                 for (int m = 0; m < 4; ++m) {
;                     const int row = row0 + ai * 128 + m * 16;
;                     const float rs = rsv[ai * 4 + m];
;                     float v[2][8];
; #pragma unroll
;                     for (int bj = 0; bj < 2; ++bj)
; #pragma unroll
;                         for (int e = 0; e < 8; ++e) v[bj][e] = acc[ai][bj][m][e >> 2][e & 3] * rs;
;                     if (pn == 2) {
;                         f16* p = V + (size_t)row * 128 + (wc - 2) * 64 + 8 * fq; *(u32x4*)p = pack8(v[0]); *(u32x4*)(p + 32) = pack8(v[1]);
;                     } else if (pn <= 4) {
; #pragma unroll
;                         for (int bj = 0; bj < 2; ++bj)
; #pragma unroll
;                             for (int e = 0; e < 8; ++e) v[bj][e] = silu_f(v[bj][e]);
;                         f16* p = GA + (size_t)row * 512 + (pn - 3) * 256 + wc * 64 + 8 * fq;
;                         *(u32x4*)p = pack8(v[0]); *(u32x4*)(p + 32) = pack8(v[1]);
;                     } else if (pn <= 6) {
; #pragma unroll
;                         for (int bj = 0; bj < 2; ++bj)
; #pragma unroll
;                             for (int e = 0; e < 8; ++e) v[bj][e] = silu_f(v[bj][e]);
;                         const int gq = 2 * (pn - 5) + (wc >> 1), cg8 = 8 * (wc & 1) + fq;
;                         f16* p = GF + ((size_t)(((row >> 12) * 4 + gq) * 16 + cg8) * 4096 + (row & 4095)) * 8;
;                         *(u32x4*)p = pack8(v[0]); *(u32x4*)(p + (size_t)4 * 4096 * 8) = pack8(v[1]);
;                     } else {
;                         const int cg8 = 8 * (wc & 1) + fq;
;                         f16* p = Z + (((size_t)(((row >> 12) * 4 + (pn - 7)) * 16 + cg8) * 4096 + (row & 4095)) * 2 + (wc >> 1)) * 8;
;                         *(u32x4*)p = pack8(v[0]); *(u32x4*)(p + (size_t)4 * 4096 * 16) = pack8(v[1]);
;                     }
.LBB0_217:
	s_cmp_gt_u32 s13, 4
	s_cselect_b64 s[82:83], -1, 0
	v_sub_co_u32_e64 v150, s[72:73], s13, 7
	s_lshl_b32 s67, s13, 1
	v_mov_b32_e32 v134, v127
	v_mov_b32_e32 v135, v128
	s_xor_b64 s[72:73], s[72:73], -1
	s_add_i32 s67, s67, s65
	s_lshl_b32 s71, s13, 9
	v_pk_mul_f32 v[140:141], v[134:135], v[178:179] op_sel_hi:[1,0]
	v_pk_mov_b32 v[134:135], v[128:129], v[122:123] op_sel:[1,0]
	s_add_u32 vcc_lo, s46, s71
	v_lshlrev_b32_e32 v130, 3, v148
	v_pk_mul_f32 v[144:145], v[134:135], v[178:179] op_sel_hi:[1,0]
	v_mov_b32_e32 v134, v123
	v_mov_b32_e32 v135, v124
	v_pk_mov_b32 v[136:137], v[96:97], v[90:91] op_sel:[1,0]
	s_addc_u32 vcc_hi, s14, 0
	v_ashrrev_i32_e32 v131, 31, v130
	v_pk_mul_f32 v[142:143], v[134:135], v[178:179] op_sel_hi:[1,0]
	v_mov_b32_e32 v134, v95
	v_mov_b32_e32 v135, v96
	v_pk_mul_f32 v[138:139], v[136:137], v[178:179] op_sel_hi:[1,0]
	v_mov_b32_e32 v136, v91
	v_mov_b32_e32 v137, v92
	v_add_u32_e32 v149, s36, v148
	v_lshl_add_u64 v[132:133], v[130:131], 1, vcc
	v_mul_f32_e32 v151, v126, v178
	v_mul_f32_e32 v152, v125, v178
	v_mul_f32_e32 v147, v94, v178
	v_pk_mul_f32 v[134:135], v[134:135], v[178:179] op_sel_hi:[1,0]
	v_pk_mul_f32 v[136:137], v[136:137], v[178:179] op_sel_hi:[1,0]
	v_mul_f32_e32 v146, v93, v178
	s_and_b64 vcc, exec, s[78:79]
	s_cbranch_vccz .LBB0_227
	s_and_b64 vcc, exec, s[82:83]
	s_cbranch_vccz .LBB0_224
	v_ashrrev_i32_e32 v153, 10, v164
	s_and_b64 vcc, exec, s[72:73]
	v_and_b32_e32 v153, 0xffffffc, v153
	s_cbranch_vccz .LBB0_221
	v_add_u32_e32 v165, v153, v150
	v_lshl_add_u32 v180, v165, 4, v149
	v_ashrrev_i32_e32 v181, 31, v180
	v_lshlrev_b64 v[180:181], 13, v[180:181]
	s_movk_i32 s10, 0xfff
	v_and_or_b32 v165, v164, s10, v180
	v_lshl_or_b32 v180, s64, 12, v165
	s_nop 0
	v_lshl_add_u64 v[184:185], v[180:181], 4, s[16:17]
	v_cvt_pk_f16_f32 v183, v143, v152
	v_cvt_pk_f16_f32 v182, v145, v142
	v_cvt_pk_f16_f32 v181, v141, v144
	v_cvt_pk_f16_f32 v180, v151, v140
	global_store_dwordx4 v[184:185], v[180:183], off
	v_add_co_u32_e32 v184, vcc, 0x80000, v184
	s_nop 0
	v_cvt_pk_f16_f32 v183, v137, v146
	v_cvt_pk_f16_f32 v182, v139, v136
	v_cvt_pk_f16_f32 v181, v135, v138
	v_cvt_pk_f16_f32 v180, v147, v134
	v_addc_co_u32_e32 v185, vcc, 0, v185, vcc
	global_store_dwordx4 v[184:185], v[180:183], off
	s_mov_b64 s[10:11], 0

; __device__ __forceinline__ float silu_f(float z) { return z * __builtin_amdgcn_rcpf(1.0f + __builtin_amdgcn_exp2f(-LOG2E * z)); }
;     __device__ __forceinline__ void operator()(const f32x4 (&acc)[2][2][4][2], const pg8::Unit& u, int ui, LAS unsigned char* lds, int wr, int wc, int fr_, int fq_) const {
;     ...
;                 for (int m = 0; m < 4; ++m) {
;                     const int row = row0 + ai * 128 + m * 16;
;                     const float rs = rsv[ai * 4 + m];
;                     float v[2][8];
; #pragma unroll
;                     for (int bj = 0; bj < 2; ++bj)
; #pragma unroll
;                         for (int e = 0; e < 8; ++e) v[bj][e] = acc[ai][bj][m][e >> 2][e & 3] * rs;
;                     if (pn == 2) {
;                         f16* p = V + (size_t)row * 128 + (wc - 2) * 64 + 8 * fq; *(u32x4*)p = pack8(v[0]); *(u32x4*)(p + 32) = pack8(v[1]);
;                     } else if (pn <= 4) {
; #pragma unroll
;                         for (int bj = 0; bj < 2; ++bj)
; #pragma unroll
;                             for (int e = 0; e < 8; ++e) v[bj][e] = silu_f(v[bj][e]);
;                         f16* p = GA + (size_t)row * 512 + (pn - 3) * 256 + wc * 64 + 8 * fq;
;                         *(u32x4*)p = pack8(v[0]); *(u32x4*)(p + 32) = pack8(v[1]);
;                     } else if (pn <= 6) {
; #pragma unroll
;                         for (int bj = 0; bj < 2; ++bj)
; #pragma unroll
;                             for (int e = 0; e < 8; ++e) v[bj][e] = silu_f(v[bj][e]);
;                         const int gq = 2 * (pn - 5) + (wc >> 1), cg8 = 8 * (wc & 1) + fq;
;                         f16* p = GF + ((size_t)(((row >> 12) * 4 + gq) * 16 + cg8) * 4096 + (row & 4095)) * 8;
;                         *(u32x4*)p = pack8(v[0]); *(u32x4*)(p + (size_t)4 * 4096 * 8) = pack8(v[1]);
;                     } else {
;                         const int cg8 = 8 * (wc & 1) + fq;
;                         f16* p = Z + (((size_t)(((row >> 12) * 4 + (pn - 7)) * 16 + cg8) * 4096 + (row & 4095)) * 2 + (wc >> 1)) * 8;
;                         *(u32x4*)p = pack8(v[0]); *(u32x4*)(p + (size_t)4 * 4096 * 16) = pack8(v[1]);
;                     }
.LBB0_229:
	s_nop 1
	v_mov_b32_e32 v134, v119
	v_mov_b32_e32 v135, v120
	v_pk_mul_f32 v[140:141], v[134:135], v[176:177] op_sel_hi:[1,0]
	v_pk_mov_b32 v[134:135], v[120:121], v[114:115] op_sel:[1,0]
	v_pk_mov_b32 v[136:137], v[88:89], v[82:83] op_sel:[1,0]
	v_pk_mul_f32 v[144:145], v[134:135], v[176:177] op_sel_hi:[1,0]
	v_mov_b32_e32 v134, v115
	v_mov_b32_e32 v135, v116
	v_pk_mul_f32 v[142:143], v[134:135], v[176:177] op_sel_hi:[1,0]
	v_mov_b32_e32 v134, v87
	v_mov_b32_e32 v135, v88
	v_pk_mul_f32 v[138:139], v[136:137], v[176:177] op_sel_hi:[1,0]
	v_mov_b32_e32 v136, v83
	v_mov_b32_e32 v137, v84
	v_cndmask_b32_e64 v147, 0, 1, s[78:79]
	v_mul_f32_e32 v153, v118, v176
	v_mul_f32_e32 v165, v117, v176
	v_mul_f32_e32 v152, v86, v176
	v_pk_mul_f32 v[134:135], v[134:135], v[176:177] op_sel_hi:[1,0]
	v_pk_mul_f32 v[136:137], v[136:137], v[176:177] op_sel_hi:[1,0]
	v_mul_f32_e32 v151, v85, v176
	v_add_u32_e32 v146, 16, v164
	v_cmp_ne_u32_e64 s[10:11], 1, v147
	s_andn2_b64 vcc, exec, s[78:79]
	s_mov_b64 s[78:79], -1
	s_cbranch_vccnz .LBB0_239
	s_andn2_b64 vcc, exec, s[82:83]
	s_cbranch_vccnz .LBB0_236
	v_ashrrev_i32_e32 v147, 10, v146
	s_andn2_b64 vcc, exec, s[72:73]
	v_and_b32_e32 v147, 0xffffffc, v147
	s_cbranch_vccnz .LBB0_233
	v_add_u32_e32 v173, v147, v150
	v_lshl_add_u32 v180, v173, 4, v149
	v_ashrrev_i32_e32 v181, 31, v180
	v_lshlrev_b64 v[180:181], 13, v[180:181]
	s_movk_i32 s71, 0xfff
	v_and_or_b32 v173, v146, s71, v180
	v_lshl_or_b32 v180, s64, 12, v173
	s_nop 0
	v_lshl_add_u64 v[184:185], v[180:181], 4, s[16:17]
	v_cvt_pk_f16_f32 v183, v143, v165
	v_cvt_pk_f16_f32 v182, v145, v142
	v_cvt_pk_f16_f32 v181, v141, v144
	v_cvt_pk_f16_f32 v180, v153, v140
	global_store_dwordx4 v[184:185], v[180:183], off
	v_add_co_u32_e32 v184, vcc, 0x80000, v184
	s_nop 0
	v_cvt_pk_f16_f32 v183, v137, v151
	v_cvt_pk_f16_f32 v182, v139, v136
	v_cvt_pk_f16_f32 v181, v135, v138
	v_cvt_pk_f16_f32 v180, v152, v134
	v_addc_co_u32_e32 v185, vcc, 0, v185, vcc
	s_mov_b64 s[78:79], 0
	global_store_dwordx4 v[184:185], v[180:183], off

; __device__ __forceinline__ float silu_f(float z) { return z * __builtin_amdgcn_rcpf(1.0f + __builtin_amdgcn_exp2f(-LOG2E * z)); }
;     __device__ __forceinline__ void operator()(const f32x4 (&acc)[2][2][4][2], const pg8::Unit& u, int ui, LAS unsigned char* lds, int wr, int wc, int fr_, int fq_) const {
;     ...
;                 for (int m = 0; m < 4; ++m) {
;                     const int row = row0 + ai * 128 + m * 16;
;                     const float rs = rsv[ai * 4 + m];
;                     float v[2][8];
; #pragma unroll
;                     for (int bj = 0; bj < 2; ++bj)
; #pragma unroll
;                         for (int e = 0; e < 8; ++e) v[bj][e] = acc[ai][bj][m][e >> 2][e & 3] * rs;
;                     if (pn == 2) {
;                         f16* p = V + (size_t)row * 128 + (wc - 2) * 64 + 8 * fq; *(u32x4*)p = pack8(v[0]); *(u32x4*)(p + 32) = pack8(v[1]);
;                     } else if (pn <= 4) {
; #pragma unroll
;                         for (int bj = 0; bj < 2; ++bj)
; #pragma unroll
;                             for (int e = 0; e < 8; ++e) v[bj][e] = silu_f(v[bj][e]);
;                         f16* p = GA + (size_t)row * 512 + (pn - 3) * 256 + wc * 64 + 8 * fq;
;                         *(u32x4*)p = pack8(v[0]); *(u32x4*)(p + 32) = pack8(v[1]);
;                     } else if (pn <= 6) {
; #pragma unroll
;                         for (int bj = 0; bj < 2; ++bj)
; #pragma unroll
;                             for (int e = 0; e < 8; ++e) v[bj][e] = silu_f(v[bj][e]);
;                         const int gq = 2 * (pn - 5) + (wc >> 1), cg8 = 8 * (wc & 1) + fq;
;                         f16* p = GF + ((size_t)(((row >> 12) * 4 + gq) * 16 + cg8) * 4096 + (row & 4095)) * 8;
;                         *(u32x4*)p = pack8(v[0]); *(u32x4*)(p + (size_t)4 * 4096 * 8) = pack8(v[1]);
;                     } else {
;                         const int cg8 = 8 * (wc & 1) + fq;
;                         f16* p = Z + (((size_t)(((row >> 12) * 4 + (pn - 7)) * 16 + cg8) * 4096 + (row & 4095)) * 2 + (wc >> 1)) * 8;
;                         *(u32x4*)p = pack8(v[0]); *(u32x4*)(p + (size_t)4 * 4096 * 16) = pack8(v[1]);
;                     }
.LBB0_241:
	s_nop 1
	v_mov_b32_e32 v134, v111
	v_mov_b32_e32 v135, v112
	v_pk_mul_f32 v[140:141], v[134:135], v[174:175] op_sel_hi:[1,0]
	v_pk_mov_b32 v[134:135], v[112:113], v[106:107] op_sel:[1,0]
	v_pk_mov_b32 v[136:137], v[80:81], v[74:75] op_sel:[1,0]
	v_pk_mul_f32 v[144:145], v[134:135], v[174:175] op_sel_hi:[1,0]
	v_mov_b32_e32 v134, v107
	v_mov_b32_e32 v135, v108
	v_pk_mul_f32 v[142:143], v[134:135], v[174:175] op_sel_hi:[1,0]
	v_mov_b32_e32 v134, v79
	v_mov_b32_e32 v135, v80
	v_pk_mul_f32 v[138:139], v[136:137], v[174:175] op_sel_hi:[1,0]
	v_mov_b32_e32 v136, v75
	v_mov_b32_e32 v137, v76
	v_mul_f32_e32 v153, v110, v174
	v_mul_f32_e32 v165, v109, v174
	v_mul_f32_e32 v152, v78, v174
	v_pk_mul_f32 v[134:135], v[134:135], v[174:175] op_sel_hi:[1,0]
	v_pk_mul_f32 v[136:137], v[136:137], v[174:175] op_sel_hi:[1,0]
	v_mul_f32_e32 v151, v77, v174
	v_add_u32_e32 v146, 32, v164
	s_and_b64 vcc, exec, s[10:11]
	s_mov_b64 s[78:79], -1
	s_cbranch_vccnz .LBB0_251
	s_andn2_b64 vcc, exec, s[82:83]
	s_cbranch_vccnz .LBB0_248
	v_ashrrev_i32_e32 v147, 10, v146
	s_andn2_b64 vcc, exec, s[72:73]
	v_and_b32_e32 v147, 0xffffffc, v147
	s_cbranch_vccnz .LBB0_245
	v_add_u32_e32 v173, v147, v150
	v_lshl_add_u32 v180, v173, 4, v149
	v_ashrrev_i32_e32 v181, 31, v180
	v_lshlrev_b64 v[180:181], 13, v[180:181]
	s_movk_i32 s71, 0xfff
	v_and_or_b32 v173, v146, s71, v180
	v_lshl_or_b32 v180, s64, 12, v173
	s_nop 0
	v_lshl_add_u64 v[184:185], v[180:181], 4, s[16:17]
	v_cvt_pk_f16_f32 v183, v143, v165
	v_cvt_pk_f16_f32 v182, v145, v142
	v_cvt_pk_f16_f32 v181, v141, v144
	v_cvt_pk_f16_f32 v180, v153, v140
	global_store_dwordx4 v[184:185], v[180:183], off
	v_add_co_u32_e32 v184, vcc, 0x80000, v184
	s_nop 0
	v_cvt_pk_f16_f32 v183, v137, v151
	v_cvt_pk_f16_f32 v182, v139, v136
	v_cvt_pk_f16_f32 v181, v135, v138
	v_cvt_pk_f16_f32 v180, v152, v134
	v_addc_co_u32_e32 v185, vcc, 0, v185, vcc
	s_mov_b64 s[78:79], 0
	global_store_dwordx4 v[184:185], v[180:183], off

; __device__ __forceinline__ float silu_f(float z) { return z * __builtin_amdgcn_rcpf(1.0f + __builtin_amdgcn_exp2f(-LOG2E * z)); }
;     __device__ __forceinline__ void operator()(const f32x4 (&acc)[2][2][4][2], const pg8::Unit& u, int ui, LAS unsigned char* lds, int wr, int wc, int fr_, int fq_) const {
;     ...
;                 for (int m = 0; m < 4; ++m) {
;                     const int row = row0 + ai * 128 + m * 16;
;                     const float rs = rsv[ai * 4 + m];
;                     float v[2][8];
; #pragma unroll
;                     for (int bj = 0; bj < 2; ++bj)
; #pragma unroll
;                         for (int e = 0; e < 8; ++e) v[bj][e] = acc[ai][bj][m][e >> 2][e & 3] * rs;
;                     if (pn == 2) {
;                         f16* p = V + (size_t)row * 128 + (wc - 2) * 64 + 8 * fq; *(u32x4*)p = pack8(v[0]); *(u32x4*)(p + 32) = pack8(v[1]);
;                     } else if (pn <= 4) {
; #pragma unroll
;                         for (int bj = 0; bj < 2; ++bj)
; #pragma unroll
;                             for (int e = 0; e < 8; ++e) v[bj][e] = silu_f(v[bj][e]);
;                         f16* p = GA + (size_t)row * 512 + (pn - 3) * 256 + wc * 64 + 8 * fq;
;                         *(u32x4*)p = pack8(v[0]); *(u32x4*)(p + 32) = pack8(v[1]);
;                     } else if (pn <= 6) {
; #pragma unroll
;                         for (int bj = 0; bj < 2; ++bj)
; #pragma unroll
;                             for (int e = 0; e < 8; ++e) v[bj][e] = silu_f(v[bj][e]);
;                         const int gq = 2 * (pn - 5) + (wc >> 1), cg8 = 8 * (wc & 1) + fq;
;                         f16* p = GF + ((size_t)(((row >> 12) * 4 + gq) * 16 + cg8) * 4096 + (row & 4095)) * 8;
;                         *(u32x4*)p = pack8(v[0]); *(u32x4*)(p + (size_t)4 * 4096 * 8) = pack8(v[1]);
;                     } else {
;                         const int cg8 = 8 * (wc & 1) + fq;
;                         f16* p = Z + (((size_t)(((row >> 12) * 4 + (pn - 7)) * 16 + cg8) * 4096 + (row & 4095)) * 2 + (wc >> 1)) * 8;
;                         *(u32x4*)p = pack8(v[0]); *(u32x4*)(p + (size_t)4 * 4096 * 16) = pack8(v[1]);
;                     }
.LBB0_253:
	s_nop 1
	v_mov_b32_e32 v134, v103
	v_mov_b32_e32 v135, v104
	v_pk_mul_f32 v[140:141], v[134:135], v[172:173] op_sel_hi:[1,0]
	v_pk_mov_b32 v[134:135], v[104:105], v[98:99] op_sel:[1,0]
	v_pk_mov_b32 v[136:137], v[72:73], v[66:67] op_sel:[1,0]
	v_pk_mul_f32 v[144:145], v[134:135], v[172:173] op_sel_hi:[1,0]
	v_mov_b32_e32 v134, v99
	v_mov_b32_e32 v135, v100
	v_pk_mul_f32 v[142:143], v[134:135], v[172:173] op_sel_hi:[1,0]
	v_mov_b32_e32 v134, v71
	v_mov_b32_e32 v135, v72
	v_pk_mul_f32 v[138:139], v[136:137], v[172:173] op_sel_hi:[1,0]
	v_mov_b32_e32 v136, v67
	v_mov_b32_e32 v137, v68
	v_mul_f32_e32 v153, v102, v172
	v_mul_f32_e32 v165, v101, v172
	v_mul_f32_e32 v152, v70, v172
	v_pk_mul_f32 v[134:135], v[134:135], v[172:173] op_sel_hi:[1,0]
	v_pk_mul_f32 v[136:137], v[136:137], v[172:173] op_sel_hi:[1,0]
	v_mul_f32_e32 v151, v69, v172
	v_add_u32_e32 v146, 48, v164
	s_and_b64 vcc, exec, s[10:11]
	s_mov_b64 s[78:79], -1
	s_cbranch_vccnz .LBB0_263
	s_andn2_b64 vcc, exec, s[82:83]
	s_cbranch_vccnz .LBB0_260
	v_ashrrev_i32_e32 v147, 10, v146
	s_andn2_b64 vcc, exec, s[72:73]
	v_and_b32_e32 v147, 0xffffffc, v147
	s_cbranch_vccnz .LBB0_257
	v_add_u32_e32 v173, v147, v150
	v_lshl_add_u32 v180, v173, 4, v149
	v_ashrrev_i32_e32 v181, 31, v180
	v_lshlrev_b64 v[180:181], 13, v[180:181]
	s_movk_i32 s71, 0xfff
	v_and_or_b32 v173, v146, s71, v180
	v_lshl_or_b32 v180, s64, 12, v173
	s_nop 0
	v_lshl_add_u64 v[184:185], v[180:181], 4, s[16:17]
	v_cvt_pk_f16_f32 v183, v143, v165
	v_cvt_pk_f16_f32 v182, v145, v142
	v_cvt_pk_f16_f32 v181, v141, v144
	v_cvt_pk_f16_f32 v180, v153, v140
	global_store_dwordx4 v[184:185], v[180:183], off
	v_add_co_u32_e32 v184, vcc, 0x80000, v184
	s_nop 0
	v_cvt_pk_f16_f32 v183, v137, v151
	v_cvt_pk_f16_f32 v182, v139, v136
	v_cvt_pk_f16_f32 v181, v135, v138
	v_cvt_pk_f16_f32 v180, v152, v134
	v_addc_co_u32_e32 v185, vcc, 0, v185, vcc
	s_mov_b64 s[78:79], 0
	global_store_dwordx4 v[184:185], v[180:183], off

; __device__ __forceinline__ float silu_f(float z) { return z * __builtin_amdgcn_rcpf(1.0f + __builtin_amdgcn_exp2f(-LOG2E * z)); }
;     __device__ __forceinline__ void operator()(const f32x4 (&acc)[2][2][4][2], const pg8::Unit& u, int ui, LAS unsigned char* lds, int wr, int wc, int fr_, int fq_) const {
;     ...
;                 for (int m = 0; m < 4; ++m) {
;                     const int row = row0 + ai * 128 + m * 16;
;                     const float rs = rsv[ai * 4 + m];
;                     float v[2][8];
; #pragma unroll
;                     for (int bj = 0; bj < 2; ++bj)
; #pragma unroll
;                         for (int e = 0; e < 8; ++e) v[bj][e] = acc[ai][bj][m][e >> 2][e & 3] * rs;
;                     if (pn == 2) {
;                         f16* p = V + (size_t)row * 128 + (wc - 2) * 64 + 8 * fq; *(u32x4*)p = pack8(v[0]); *(u32x4*)(p + 32) = pack8(v[1]);
;                     } else if (pn <= 4) {
; #pragma unroll
;                         for (int bj = 0; bj < 2; ++bj)
; #pragma unroll
;                             for (int e = 0; e < 8; ++e) v[bj][e] = silu_f(v[bj][e]);
;                         f16* p = GA + (size_t)row * 512 + (pn - 3) * 256 + wc * 64 + 8 * fq;
;                         *(u32x4*)p = pack8(v[0]); *(u32x4*)(p + 32) = pack8(v[1]);
;                     } else if (pn <= 6) {
; #pragma unroll
;                         for (int bj = 0; bj < 2; ++bj)
; #pragma unroll
;                             for (int e = 0; e < 8; ++e) v[bj][e] = silu_f(v[bj][e]);
;                         const int gq = 2 * (pn - 5) + (wc >> 1), cg8 = 8 * (wc & 1) + fq;
;                         f16* p = GF + ((size_t)(((row >> 12) * 4 + gq) * 16 + cg8) * 4096 + (row & 4095)) * 8;
;                         *(u32x4*)p = pack8(v[0]); *(u32x4*)(p + (size_t)4 * 4096 * 8) = pack8(v[1]);
;                     } else {
;                         const int cg8 = 8 * (wc & 1) + fq;
;                         f16* p = Z + (((size_t)(((row >> 12) * 4 + (pn - 7)) * 16 + cg8) * 4096 + (row & 4095)) * 2 + (wc >> 1)) * 8;
;                         *(u32x4*)p = pack8(v[0]); *(u32x4*)(p + (size_t)4 * 4096 * 16) = pack8(v[1]);
;                     }
.LBB0_265:
	s_nop 1
	v_mov_b32_e32 v134, v63
	v_mov_b32_e32 v135, v64
	v_pk_mul_f32 v[140:141], v[134:135], v[170:171] op_sel_hi:[1,0]
	v_pk_mov_b32 v[134:135], v[64:65], v[58:59] op_sel:[1,0]
	v_pk_mov_b32 v[136:137], v[32:33], v[26:27] op_sel:[1,0]
	v_pk_mul_f32 v[146:147], v[134:135], v[170:171] op_sel_hi:[1,0]
	v_mov_b32_e32 v134, v59
	v_mov_b32_e32 v135, v60
	v_pk_mul_f32 v[142:143], v[134:135], v[170:171] op_sel_hi:[1,0]
	v_mov_b32_e32 v134, v31
	v_mov_b32_e32 v135, v32
	v_pk_mul_f32 v[138:139], v[136:137], v[170:171] op_sel_hi:[1,0]
	v_mov_b32_e32 v136, v27
	v_mov_b32_e32 v137, v28
	v_add_u32_e32 v144, 0x80, v164
	v_mul_f32_e32 v153, v62, v170
	v_mul_f32_e32 v165, v61, v170
	v_mul_f32_e32 v152, v30, v170
	v_pk_mul_f32 v[134:135], v[134:135], v[170:171] op_sel_hi:[1,0]
	v_pk_mul_f32 v[136:137], v[136:137], v[170:171] op_sel_hi:[1,0]
	v_mul_f32_e32 v151, v29, v170
	s_and_b64 vcc, exec, s[10:11]
	s_mov_b64 s[78:79], -1
	s_cbranch_vccnz .LBB0_275
	s_andn2_b64 vcc, exec, s[82:83]
	s_cbranch_vccnz .LBB0_272
	v_ashrrev_i32_e32 v145, 10, v144
	s_andn2_b64 vcc, exec, s[72:73]
	v_and_b32_e32 v145, 0xffffffc, v145
	s_cbranch_vccnz .LBB0_269
	v_add_u32_e32 v173, v145, v150
	v_lshl_add_u32 v180, v173, 4, v149
	v_ashrrev_i32_e32 v181, 31, v180
	v_lshlrev_b64 v[180:181], 13, v[180:181]
	s_movk_i32 s71, 0xfff
	v_and_or_b32 v173, v144, s71, v180
	v_lshl_or_b32 v180, s64, 12, v173
	s_nop 0
	v_lshl_add_u64 v[184:185], v[180:181], 4, s[16:17]
	v_cvt_pk_f16_f32 v183, v143, v165
	v_cvt_pk_f16_f32 v182, v147, v142
	v_cvt_pk_f16_f32 v181, v141, v146
	v_cvt_pk_f16_f32 v180, v153, v140
	global_store_dwordx4 v[184:185], v[180:183], off
	v_add_co_u32_e32 v184, vcc, 0x80000, v184
	s_nop 0
	v_cvt_pk_f16_f32 v183, v137, v151
	v_cvt_pk_f16_f32 v182, v139, v136
	v_cvt_pk_f16_f32 v181, v135, v138
	v_cvt_pk_f16_f32 v180, v152, v134
	v_addc_co_u32_e32 v185, vcc, 0, v185, vcc
	s_mov_b64 s[78:79], 0
	global_store_dwordx4 v[184:185], v[180:183], off

; __device__ __forceinline__ float silu_f(float z) { return z * __builtin_amdgcn_rcpf(1.0f + __builtin_amdgcn_exp2f(-LOG2E * z)); }
;     __device__ __forceinline__ void operator()(const f32x4 (&acc)[2][2][4][2], const pg8::Unit& u, int ui, LAS unsigned char* lds, int wr, int wc, int fr_, int fq_) const {
;     ...
;                 for (int m = 0; m < 4; ++m) {
;                     const int row = row0 + ai * 128 + m * 16;
;                     const float rs = rsv[ai * 4 + m];
;                     float v[2][8];
; #pragma unroll
;                     for (int bj = 0; bj < 2; ++bj)
; #pragma unroll
;                         for (int e = 0; e < 8; ++e) v[bj][e] = acc[ai][bj][m][e >> 2][e & 3] * rs;
;                     if (pn == 2) {
;                         f16* p = V + (size_t)row * 128 + (wc - 2) * 64 + 8 * fq; *(u32x4*)p = pack8(v[0]); *(u32x4*)(p + 32) = pack8(v[1]);
;                     } else if (pn <= 4) {
; #pragma unroll
;                         for (int bj = 0; bj < 2; ++bj)
; #pragma unroll
;                             for (int e = 0; e < 8; ++e) v[bj][e] = silu_f(v[bj][e]);
;                         f16* p = GA + (size_t)row * 512 + (pn - 3) * 256 + wc * 64 + 8 * fq;
;                         *(u32x4*)p = pack8(v[0]); *(u32x4*)(p + 32) = pack8(v[1]);
;                     } else if (pn <= 6) {
; #pragma unroll
;                         for (int bj = 0; bj < 2; ++bj)
; #pragma unroll
;                             for (int e = 0; e < 8; ++e) v[bj][e] = silu_f(v[bj][e]);
;                         const int gq = 2 * (pn - 5) + (wc >> 1), cg8 = 8 * (wc & 1) + fq;
;                         f16* p = GF + ((size_t)(((row >> 12) * 4 + gq) * 16 + cg8) * 4096 + (row & 4095)) * 8;
;                         *(u32x4*)p = pack8(v[0]); *(u32x4*)(p + (size_t)4 * 4096 * 8) = pack8(v[1]);
;                     } else {
;                         const int cg8 = 8 * (wc & 1) + fq;
;                         f16* p = Z + (((size_t)(((row >> 12) * 4 + (pn - 7)) * 16 + cg8) * 4096 + (row & 4095)) * 2 + (wc >> 1)) * 8;
;                         *(u32x4*)p = pack8(v[0]); *(u32x4*)(p + (size_t)4 * 4096 * 16) = pack8(v[1]);
;                     }
.LBB0_277:
	s_nop 1
	v_mov_b32_e32 v134, v55
	v_mov_b32_e32 v135, v56
	v_pk_mul_f32 v[140:141], v[134:135], v[168:169] op_sel_hi:[1,0]
	v_pk_mov_b32 v[134:135], v[56:57], v[50:51] op_sel:[1,0]
	v_pk_mov_b32 v[136:137], v[24:25], v[18:19] op_sel:[1,0]
	v_pk_mul_f32 v[144:145], v[134:135], v[168:169] op_sel_hi:[1,0]
	v_mov_b32_e32 v134, v51
	v_mov_b32_e32 v135, v52
	v_pk_mul_f32 v[142:143], v[134:135], v[168:169] op_sel_hi:[1,0]
	v_mov_b32_e32 v134, v23
	v_mov_b32_e32 v135, v24
	v_pk_mul_f32 v[138:139], v[136:137], v[168:169] op_sel_hi:[1,0]
	v_mov_b32_e32 v136, v19
	v_mov_b32_e32 v137, v20
	v_mul_f32_e32 v153, v54, v168
	v_mul_f32_e32 v165, v53, v168
	v_mul_f32_e32 v152, v22, v168
	v_pk_mul_f32 v[134:135], v[134:135], v[168:169] op_sel_hi:[1,0]
	v_pk_mul_f32 v[136:137], v[136:137], v[168:169] op_sel_hi:[1,0]
	v_mul_f32_e32 v151, v21, v168
	v_add_u32_e32 v146, 0x90, v164
	s_and_b64 vcc, exec, s[10:11]
	s_mov_b64 s[78:79], -1
	s_cbranch_vccnz .LBB0_287
	s_andn2_b64 vcc, exec, s[82:83]
	s_cbranch_vccnz .LBB0_284
	v_ashrrev_i32_e32 v147, 10, v146
	s_andn2_b64 vcc, exec, s[72:73]
	v_and_b32_e32 v147, 0xffffffc, v147
	s_cbranch_vccnz .LBB0_281
	v_add_u32_e32 v173, v147, v150
	v_lshl_add_u32 v180, v173, 4, v149
	v_ashrrev_i32_e32 v181, 31, v180
	v_lshlrev_b64 v[180:181], 13, v[180:181]
	s_movk_i32 s71, 0xfff
	v_and_or_b32 v173, v146, s71, v180
	v_lshl_or_b32 v180, s64, 12, v173
	s_nop 0
	v_lshl_add_u64 v[184:185], v[180:181], 4, s[16:17]
	v_cvt_pk_f16_f32 v183, v143, v165
	v_cvt_pk_f16_f32 v182, v145, v142
	v_cvt_pk_f16_f32 v181, v141, v144
	v_cvt_pk_f16_f32 v180, v153, v140
	global_store_dwordx4 v[184:185], v[180:183], off
	v_add_co_u32_e32 v184, vcc, 0x80000, v184
	s_nop 0
	v_cvt_pk_f16_f32 v183, v137, v151
	v_cvt_pk_f16_f32 v182, v139, v136
	v_cvt_pk_f16_f32 v181, v135, v138
	v_cvt_pk_f16_f32 v180, v152, v134
	v_addc_co_u32_e32 v185, vcc, 0, v185, vcc
	s_mov_b64 s[78:79], 0
	global_store_dwordx4 v[184:185], v[180:183], off

; __device__ __forceinline__ float silu_f(float z) { return z * __builtin_amdgcn_rcpf(1.0f + __builtin_amdgcn_exp2f(-LOG2E * z)); }
;     __device__ __forceinline__ void operator()(const f32x4 (&acc)[2][2][4][2], const pg8::Unit& u, int ui, LAS unsigned char* lds, int wr, int wc, int fr_, int fq_) const {
;     ...
;                 for (int m = 0; m < 4; ++m) {
;                     const int row = row0 + ai * 128 + m * 16;
;                     const float rs = rsv[ai * 4 + m];
;                     float v[2][8];
; #pragma unroll
;                     for (int bj = 0; bj < 2; ++bj)
; #pragma unroll
;                         for (int e = 0; e < 8; ++e) v[bj][e] = acc[ai][bj][m][e >> 2][e & 3] * rs;
;                     if (pn == 2) {
;                         f16* p = V + (size_t)row * 128 + (wc - 2) * 64 + 8 * fq; *(u32x4*)p = pack8(v[0]); *(u32x4*)(p + 32) = pack8(v[1]);
;                     } else if (pn <= 4) {
; #pragma unroll
;                         for (int bj = 0; bj < 2; ++bj)
; #pragma unroll
;                             for (int e = 0; e < 8; ++e) v[bj][e] = silu_f(v[bj][e]);
;                         f16* p = GA + (size_t)row * 512 + (pn - 3) * 256 + wc * 64 + 8 * fq;
;                         *(u32x4*)p = pack8(v[0]); *(u32x4*)(p + 32) = pack8(v[1]);
;                     } else if (pn <= 6) {
; #pragma unroll
;                         for (int bj = 0; bj < 2; ++bj)
; #pragma unroll
;                             for (int e = 0; e < 8; ++e) v[bj][e] = silu_f(v[bj][e]);
;                         const int gq = 2 * (pn - 5) + (wc >> 1), cg8 = 8 * (wc & 1) + fq;
;                         f16* p = GF + ((size_t)(((row >> 12) * 4 + gq) * 16 + cg8) * 4096 + (row & 4095)) * 8;
;                         *(u32x4*)p = pack8(v[0]); *(u32x4*)(p + (size_t)4 * 4096 * 8) = pack8(v[1]);
;                     } else {
;                         const int cg8 = 8 * (wc & 1) + fq;
;                         f16* p = Z + (((size_t)(((row >> 12) * 4 + (pn - 7)) * 16 + cg8) * 4096 + (row & 4095)) * 2 + (wc >> 1)) * 8;
;                         *(u32x4*)p = pack8(v[0]); *(u32x4*)(p + (size_t)4 * 4096 * 16) = pack8(v[1]);
;                     }
.LBB0_289:
	s_nop 1
	v_mov_b32_e32 v134, v47
	v_mov_b32_e32 v135, v48
	v_pk_mul_f32 v[140:141], v[134:135], v[166:167] op_sel_hi:[1,0]
	v_pk_mov_b32 v[134:135], v[48:49], v[42:43] op_sel:[1,0]
	v_pk_mov_b32 v[136:137], v[16:17], v[10:11] op_sel:[1,0]
	v_pk_mul_f32 v[144:145], v[134:135], v[166:167] op_sel_hi:[1,0]
	v_mov_b32_e32 v134, v43
	v_mov_b32_e32 v135, v44
	v_pk_mul_f32 v[142:143], v[134:135], v[166:167] op_sel_hi:[1,0]
	v_mov_b32_e32 v134, v15
	v_mov_b32_e32 v135, v16
	v_pk_mul_f32 v[138:139], v[136:137], v[166:167] op_sel_hi:[1,0]
	v_mov_b32_e32 v136, v11
	v_mov_b32_e32 v137, v12
	v_mul_f32_e32 v153, v46, v166
	v_mul_f32_e32 v165, v45, v166
	v_mul_f32_e32 v152, v14, v166
	v_pk_mul_f32 v[134:135], v[134:135], v[166:167] op_sel_hi:[1,0]
	v_pk_mul_f32 v[136:137], v[136:137], v[166:167] op_sel_hi:[1,0]
	v_mul_f32_e32 v151, v13, v166
	v_add_u32_e32 v146, 0xa0, v164
	s_and_b64 vcc, exec, s[10:11]
	s_mov_b64 s[78:79], -1
	s_cbranch_vccnz .LBB0_299
	s_andn2_b64 vcc, exec, s[82:83]
	s_cbranch_vccnz .LBB0_296
	v_ashrrev_i32_e32 v147, 10, v146
	s_andn2_b64 vcc, exec, s[72:73]
	v_and_b32_e32 v147, 0xffffffc, v147
	s_cbranch_vccnz .LBB0_293
	v_add_u32_e32 v173, v147, v150
	v_lshl_add_u32 v180, v173, 4, v149
	v_ashrrev_i32_e32 v181, 31, v180
	v_lshlrev_b64 v[180:181], 13, v[180:181]
	s_movk_i32 s71, 0xfff
	v_and_or_b32 v173, v146, s71, v180
	v_lshl_or_b32 v180, s64, 12, v173
	s_nop 0
	v_lshl_add_u64 v[184:185], v[180:181], 4, s[16:17]
	v_cvt_pk_f16_f32 v183, v143, v165
	v_cvt_pk_f16_f32 v182, v145, v142
	v_cvt_pk_f16_f32 v181, v141, v144
	v_cvt_pk_f16_f32 v180, v153, v140
	global_store_dwordx4 v[184:185], v[180:183], off
	v_add_co_u32_e32 v184, vcc, 0x80000, v184
	s_nop 0
	v_cvt_pk_f16_f32 v183, v137, v151
	v_cvt_pk_f16_f32 v182, v139, v136
	v_cvt_pk_f16_f32 v181, v135, v138
	v_cvt_pk_f16_f32 v180, v152, v134
	v_addc_co_u32_e32 v185, vcc, 0, v185, vcc
	s_mov_b64 s[78:79], 0
	global_store_dwordx4 v[184:185], v[180:183], off

; __device__ __forceinline__ float silu_f(float z) { return z * __builtin_amdgcn_rcpf(1.0f + __builtin_amdgcn_exp2f(-LOG2E * z)); }
;     __device__ __forceinline__ void operator()(const f32x4 (&acc)[2][2][4][2], const pg8::Unit& u, int ui, LAS unsigned char* lds, int wr, int wc, int fr_, int fq_) const {
;     ...
;                 for (int m = 0; m < 4; ++m) {
;                     const int row = row0 + ai * 128 + m * 16;
;                     const float rs = rsv[ai * 4 + m];
;                     float v[2][8];
; #pragma unroll
;                     for (int bj = 0; bj < 2; ++bj)
; #pragma unroll
;                         for (int e = 0; e < 8; ++e) v[bj][e] = acc[ai][bj][m][e >> 2][e & 3] * rs;
;                     if (pn == 2) {
;                         f16* p = V + (size_t)row * 128 + (wc - 2) * 64 + 8 * fq; *(u32x4*)p = pack8(v[0]); *(u32x4*)(p + 32) = pack8(v[1]);
;                     } else if (pn <= 4) {
; #pragma unroll
;                         for (int bj = 0; bj < 2; ++bj)
; #pragma unroll
;                             for (int e = 0; e < 8; ++e) v[bj][e] = silu_f(v[bj][e]);
;                         f16* p = GA + (size_t)row * 512 + (pn - 3) * 256 + wc * 64 + 8 * fq;
;                         *(u32x4*)p = pack8(v[0]); *(u32x4*)(p + 32) = pack8(v[1]);
;                     } else if (pn <= 6) {
; #pragma unroll
;                         for (int bj = 0; bj < 2; ++bj)
; #pragma unroll
;                             for (int e = 0; e < 8; ++e) v[bj][e] = silu_f(v[bj][e]);
;                         const int gq = 2 * (pn - 5) + (wc >> 1), cg8 = 8 * (wc & 1) + fq;
;                         f16* p = GF + ((size_t)(((row >> 12) * 4 + gq) * 16 + cg8) * 4096 + (row & 4095)) * 8;
;                         *(u32x4*)p = pack8(v[0]); *(u32x4*)(p + (size_t)4 * 4096 * 8) = pack8(v[1]);
;                     } else {
;                         const int cg8 = 8 * (wc & 1) + fq;
;                         f16* p = Z + (((size_t)(((row >> 12) * 4 + (pn - 7)) * 16 + cg8) * 4096 + (row & 4095)) * 2 + (wc >> 1)) * 8;
;                         *(u32x4*)p = pack8(v[0]); *(u32x4*)(p + (size_t)4 * 4096 * 16) = pack8(v[1]);
;                     }
.LBB0_301:
	s_nop 1
	v_mov_b32_e32 v134, v39
	v_mov_b32_e32 v135, v40
	v_pk_mul_f32 v[140:141], v[134:135], v[162:163] op_sel_hi:[1,0]
	v_pk_mov_b32 v[134:135], v[40:41], v[34:35] op_sel:[1,0]
	v_pk_mov_b32 v[136:137], v[8:9], v[2:3] op_sel:[1,0]
	v_pk_mul_f32 v[144:145], v[134:135], v[162:163] op_sel_hi:[1,0]
	v_mov_b32_e32 v134, v35
	v_mov_b32_e32 v135, v36
	v_pk_mul_f32 v[142:143], v[134:135], v[162:163] op_sel_hi:[1,0]
	v_mov_b32_e32 v134, v7
	v_mov_b32_e32 v135, v8
	v_pk_mul_f32 v[138:139], v[136:137], v[162:163] op_sel_hi:[1,0]
	v_mov_b32_e32 v136, v3
	v_mov_b32_e32 v137, v4
	v_mul_f32_e32 v153, v38, v162
	v_mul_f32_e32 v165, v37, v162
	v_mul_f32_e32 v152, v6, v162
	v_pk_mul_f32 v[134:135], v[134:135], v[162:163] op_sel_hi:[1,0]
	v_pk_mul_f32 v[136:137], v[136:137], v[162:163] op_sel_hi:[1,0]
	v_mul_f32_e32 v151, v5, v162
	v_add_u32_e32 v146, 0xb0, v164
	s_and_b64 vcc, exec, s[10:11]
	s_mov_b64 s[10:11], -1
	s_cbranch_vccnz .LBB0_311
	s_andn2_b64 vcc, exec, s[82:83]
	s_cbranch_vccnz .LBB0_308
	v_ashrrev_i32_e32 v147, 10, v146
	s_andn2_b64 vcc, exec, s[72:73]
	v_and_b32_e32 v147, 0xffffffc, v147
	s_cbranch_vccnz .LBB0_305
	v_add_u32_e32 v150, v147, v150
	v_lshl_add_u32 v180, v150, 4, v149
	v_ashrrev_i32_e32 v181, 31, v180
	v_lshlrev_b64 v[180:181], 13, v[180:181]
	s_movk_i32 s10, 0xfff
	v_and_or_b32 v150, v146, s10, v180
	v_lshl_or_b32 v180, s64, 12, v150
	s_nop 0
	v_lshl_add_u64 v[184:185], v[180:181], 4, s[16:17]
	v_cvt_pk_f16_f32 v183, v143, v165
	v_cvt_pk_f16_f32 v182, v145, v142
	v_cvt_pk_f16_f32 v181, v141, v144
	v_cvt_pk_f16_f32 v180, v153, v140
	global_store_dwordx4 v[184:185], v[180:183], off
	v_add_co_u32_e32 v184, vcc, 0x80000, v184
	s_nop 0
	v_cvt_pk_f16_f32 v183, v137, v151
	v_cvt_pk_f16_f32 v182, v139, v136
	v_cvt_pk_f16_f32 v181, v135, v138
	v_cvt_pk_f16_f32 v180, v152, v134
	v_addc_co_u32_e32 v185, vcc, 0, v185, vcc
	s_mov_b64 s[10:11], 0
	global_store_dwordx4 v[184:185], v[180:183], off

; __device__ __forceinline__ void gemm1_tail_quadrant(LAS unsigned char* lds, const f16* A, const f16* Bt, unsigned char* ws, int pm, int pn, int ai, int bj) {
;     ...
;     const float* SS = (const float*)(ws + WS_SS); f16* Z = (f16*)(ws + WS_Z);
;     const int row0 = pm * 256 + ai * 128 + wr * 64 + fr;
;     f32x4 part[4];
; #pragma unroll
;     for (int m = 0; m < 4; ++m) part[m] = *(const f32x4*)(SS + (size_t)(row0 + m * 16) * 16 + 4 * fq);
; #pragma unroll
;     for (int m = 0; m < 4; ++m) {
;         float t = (part[m][0] + part[m][1]) + (part[m][2] + part[m][3]);
;         t = sum_fq(t);
;         const float rs = __builtin_amdgcn_rsqf(t * (1.0f / 1024.0f) + EPS);
;         const int row = row0 + m * 16;
;         float v[8];
; #pragma unroll
;         for (int e = 0; e < 8; ++e) v[e] = acc[m][e >> 2][e & 3] * rs;
;         const int cg8 = 8 * (wc & 1) + 4 * bj + fq;
;         f16* p = Z + (((size_t)(((row >> 12) * 4 + (pn - 7)) * 16 + cg8) * 4096 + (row & 4095)) * 2 + (wc >> 1)) * 8;
;         *(u32x4*)p = pack8(v);
;     }
;     asm volatile("s_waitcnt vmcnt(0)" ::: "memory");
;     __syncthreads();
.LBB0_319:
	s_and_b32 s4, 0xffff, s14
	s_lshl_b32 s6, s13, 7
	s_lshl_b32 s4, s4, 8
	s_or_b32 s4, s4, s6
	s_add_i32 s4, s4, s31
	v_or_b32_e32 v54, s4, v23
	v_readlane_b32 s6, v254, 4
	v_mov_b32_e32 v23, v195
	v_readlane_b32 s7, v254, 5
	v_ashrrev_i32_e32 v55, 31, v54
	v_lshlrev_b64 v[24:25], 6, v[54:55]
	v_lshl_add_u64 v[22:23], s[6:7], 0, v[22:23]
	v_lshl_add_u64 v[24:25], v[22:23], 0, v[24:25]
	global_load_dwordx4 v[46:49], v[24:25], off
	v_or_b32_e32 v24, 16, v54
	v_ashrrev_i32_e32 v25, 31, v24
	v_lshlrev_b64 v[24:25], 6, v[24:25]
	v_lshl_add_u64 v[24:25], v[22:23], 0, v[24:25]
	global_load_dwordx4 v[50:53], v[24:25], off
	v_or_b32_e32 v24, 32, v54
	v_ashrrev_i32_e32 v25, 31, v24
	v_lshlrev_b64 v[24:25], 6, v[24:25]
	v_lshl_add_u64 v[24:25], v[22:23], 0, v[24:25]
	global_load_dwordx4 v[30:33], v[24:25], off
	v_or_b32_e32 v24, 48, v54
	v_ashrrev_i32_e32 v25, 31, v24
	v_lshlrev_b64 v[24:25], 6, v[24:25]
	v_lshl_add_u64 v[22:23], v[22:23], 0, v[24:25]
	global_load_dwordx4 v[22:25], v[22:23], off
	s_ashr_i32 s4, s4, 10
	s_and_b32 s5, 0xffff, s15
	s_lshl_b32 s6, s12, 3
	s_and_b32 s4, s4, 0xffffffc
	s_and_b32 s6, s6, 8
	s_lshl_b32 s7, s11, 2
	s_add_i32 s5, s5, s4
	s_or_b32 s6, s6, s7
	s_lshl_b32 s4, s5, 4
	s_or_b32 s4, s4, s6
	s_addk_i32 s4, 0xff90
	v_or_b32_e32 v42, s4, v44
	v_mov_b32_e32 v44, v54
	v_and_b32_e32 v45, 0xfcf, v44
	v_ashrrev_i32_e32 v43, 31, v42
	v_lshlrev_b64 v[42:43], 13, v[42:43]
	s_lshr_b32 s4, s10, 1
	s_lshl_b32 s4, s4, 12
	v_or3_b32 v42, v42, s4, v45
	s_mov_b64 s[4:5], 0
	s_waitcnt vmcnt(0)
	v_add_f32_e32 v44, v46, v47
	v_add_f32_e32 v46, v48, v49
	v_add_f32_e32 v44, v44, v46
	v_mov_b32_e32 v46, v44
	s_nop 1
	v_permlane16_swap_b32_e32 v44, v46
	v_add_f32_e32 v44, v44, v46
	v_mov_b32_e32 v46, v44
	s_nop 1
	v_permlane32_swap_b32_e32 v44, v46
	v_add_f32_e32 v44, v44, v46
	v_fmamk_f32 v44, v44, 0x3a800000, v1
	v_rsq_f32_e32 v44, v44
	v_lshl_add_u64 v[46:47], v[42:43], 4, s[16:17]
	v_fma_mixlo_f16 v45, v38, v44, 0
	v_mov_b32_e32 v38, v39
	v_mov_b32_e32 v39, v40
	v_pk_mov_b32 v[40:41], v[40:41], v[34:35] op_sel:[1,0]
	v_mov_b32_e32 v34, v35
	v_mov_b32_e32 v35, v36
	v_pk_mul_f32 v[38:39], v[38:39], v[44:45] op_sel_hi:[1,0]
	v_pk_mul_f32 v[40:41], v[40:41], v[44:45] op_sel_hi:[1,0]
	v_pk_mul_f32 v[34:35], v[34:35], v[44:45] op_sel_hi:[1,0]
	v_cvt_pk_f16_f32 v39, v38, v39
	v_cvt_pk_f16_f32 v40, v40, v41
	v_cvt_pk_f16_f32 v34, v34, v35
	v_pack_b32_f16 v38, v45, v39
	v_alignbit_b32 v39, v40, v39, 16
	v_alignbit_b32 v40, v34, v40, 16
	v_lshrrev_b32_e32 v41, 16, v34
	v_add_f32_e32 v34, v50, v51
	v_add_f32_e32 v35, v52, v53
	v_add_f32_e32 v34, v34, v35
	v_mov_b32_e32 v35, v34
	s_nop 1
	v_permlane16_swap_b32_e32 v34, v35
	v_add_f32_e32 v34, v34, v35
	v_mov_b32_e32 v35, v34
	s_nop 1
	v_permlane32_swap_b32_e32 v34, v35
	v_add_f32_e32 v34, v34, v35
	v_fmamk_f32 v34, v34, 0x3a800000, v1
	v_rsq_f32_e32 v36, v34
	v_fma_mixhi_f16 v41, v37, v44, 0
	v_or_b32_e32 v34, 16, v42
	v_mov_b32_e32 v35, v43
	v_fma_mixlo_f16 v37, v26, v36, 0
	v_mov_b32_e32 v26, v27
	v_mov_b32_e32 v27, v28
	v_pk_mov_b32 v[28:29], v[28:29], v[18:19] op_sel:[1,0]
	v_mov_b32_e32 v18, v19
	v_mov_b32_e32 v19, v20
	v_pk_mul_f32 v[26:27], v[26:27], v[36:37] op_sel_hi:[1,0]
	v_pk_mul_f32 v[28:29], v[28:29], v[36:37] op_sel_hi:[1,0]
	v_pk_mul_f32 v[18:19], v[18:19], v[36:37] op_sel_hi:[1,0]
	v_cvt_pk_f16_f32 v27, v26, v27
	v_cvt_pk_f16_f32 v28, v28, v29
	v_cvt_pk_f16_f32 v18, v18, v19
	v_pack_b32_f16 v26, v37, v27
	v_alignbit_b32 v27, v28, v27, 16
	v_alignbit_b32 v28, v18, v28, 16
	v_lshrrev_b32_e32 v29, 16, v18
	v_add_f32_e32 v18, v30, v31
	v_add_f32_e32 v19, v32, v33
	v_add_f32_e32 v18, v18, v19
	v_mov_b32_e32 v19, v18
	s_nop 1
	v_permlane16_swap_b32_e32 v18, v19
	v_add_f32_e32 v18, v18, v19
	v_mov_b32_e32 v19, v18
	s_nop 1
	v_permlane32_swap_b32_e32 v18, v19
	v_add_f32_e32 v18, v18, v19
	v_fmamk_f32 v18, v18, 0x3a800000, v1
	v_rsq_f32_e32 v18, v18
	v_fma_mixhi_f16 v29, v21, v36, 0
	v_or_b32_e32 v20, 32, v42
	v_mov_b32_e32 v21, v43
	v_fma_mixlo_f16 v19, v14, v18, 0
	v_mov_b32_e32 v14, v15
	v_mov_b32_e32 v15, v16
	v_pk_mov_b32 v[16:17], v[16:17], v[10:11] op_sel:[1,0]
	v_mov_b32_e32 v10, v11
	v_mov_b32_e32 v11, v12
	v_pk_mul_f32 v[14:15], v[14:15], v[18:19] op_sel_hi:[1,0]
	v_pk_mul_f32 v[16:17], v[16:17], v[18:19] op_sel_hi:[1,0]
	v_pk_mul_f32 v[10:11], v[10:11], v[18:19] op_sel_hi:[1,0]
	v_cvt_pk_f16_f32 v15, v14, v15
	v_cvt_pk_f16_f32 v16, v16, v17
	v_cvt_pk_f16_f32 v10, v10, v11
	v_pack_b32_f16 v14, v19, v15
	v_alignbit_b32 v15, v16, v15, 16
	v_alignbit_b32 v16, v10, v16, 16
	v_lshrrev_b32_e32 v17, 16, v10
	v_add_f32_e32 v10, v22, v23
	v_add_f32_e32 v11, v24, v25
	v_add_f32_e32 v10, v10, v11
	v_mov_b32_e32 v11, v10
	s_nop 1
	v_permlane16_swap_b32_e32 v10, v11
	v_add_f32_e32 v10, v10, v11
	v_mov_b32_e32 v11, v10
	s_nop 1
	v_permlane32_swap_b32_e32 v10, v11
	v_add_f32_e32 v10, v10, v11
	v_fmamk_f32 v10, v10, 0x3a800000, v1
	v_rsq_f32_e32 v10, v10
	v_or_b32_e32 v42, 48, v42
	v_lshl_add_u64 v[34:35], v[34:35], 4, s[16:17]
	v_lshl_add_u64 v[20:21], v[20:21], 4, s[16:17]
	v_fma_mixlo_f16 v11, v2, v10, 0
	v_mov_b32_e32 v2, v3
	v_mov_b32_e32 v3, v4
	v_pk_mov_b32 v[4:5], v[4:5], v[6:7] op_sel:[1,0]
	v_pk_mul_f32 v[2:3], v[2:3], v[10:11] op_sel_hi:[1,0]
	v_pk_mul_f32 v[4:5], v[4:5], v[10:11] op_sel_hi:[1,0]
	v_cvt_pk_f16_f32 v3, v2, v3
	v_cvt_pk_f16_f32 v6, v4, v5
	v_mov_b32_e32 v4, v7
	v_mov_b32_e32 v5, v8
	v_pk_mul_f32 v[4:5], v[4:5], v[10:11] op_sel_hi:[1,0]
	v_fma_mixhi_f16 v17, v13, v18, 0
	v_cvt_pk_f16_f32 v5, v4, v5
	v_alignbit_b32 v4, v5, v6, 16
	v_lshrrev_b32_e32 v5, 16, v5
	v_lshl_add_u64 v[12:13], v[42:43], 4, s[16:17]
	v_pack_b32_f16 v2, v11, v3
	v_alignbit_b32 v3, v6, v3, 16
	v_fma_mixhi_f16 v5, v9, v10, 0
	global_store_dwordx4 v[46:47], v[38:41], off
	global_store_dwordx4 v[34:35], v[26:29], off
	global_store_dwordx4 v[20:21], v[14:17], off
	global_store_dwordx4 v[12:13], v[2:5], off
	s_waitcnt vmcnt(0)
	s_barrier

; __device__ void fft_phase(const Args& a, LAS unsigned char* lds) {
;     ...
;     FFT_LOAD(unit);
; #pragma unroll 1
;     for (; unit < 768; unit += G) {
;     const int cg8 = unit & 15, g = (unit >> 4) & 3, b = unit >> 6;
;     const size_t blk0 = (size_t)((b * 4 + g) * 16 + cg8) * 4096;
;     __syncthreads();
; #pragma unroll
;     for (int it = 0; it < 4; ++it) {
;         const int token = 2 * (tid + NTHREADS * it);
;         const int n1 = token >> 6, n2 = token & 63;
;         const int off = n1 * 128 + (((n2 >> 4) ^ (n1 & 3)) << 5) + (n2 & 15) * 2;
.LBB0_389:
	s_cmp_lg_u32 s0, s85
	s_mov_b64 s[0:1], -1
	s_cbranch_scc0 .LBB0_394
	v_mov_b32_e32 v178, v0
	s_andn2_b64 vcc, exec, s[92:93]
	v_readfirstlane_b32 s0, v178
	s_cbranch_vccnz .LBB0_393
	s_waitcnt vmcnt(0)
	v_mov_b32_e32 v2, v178
	s_load_dword s4, s[86:87], 0x0
	v_bfe_u32 v68, v178, 3, 28
	v_lshlrev_b32_e32 v50, 1, v2
	v_add_u32_e32 v2, 0xc00, v50
	v_add_u32_e32 v18, 0x800, v50
	v_add_u32_e32 v34, 0x400, v50
	v_ashrrev_i32_e32 v3, 31, v2
	v_ashrrev_i32_e32 v19, 31, v18
	v_ashrrev_i32_e32 v35, 31, v34
	s_waitcnt lgkmcnt(0)
	v_ashrrev_i32_e32 v51, 31, v50
	v_lshl_add_u64 v[2:3], s[90:91], 1, v[2:3]
	v_lshl_add_u64 v[18:19], s[90:91], 1, v[18:19]
	v_lshl_add_u64 v[34:35], s[90:91], 1, v[34:35]
	v_lshl_add_u64 v[50:51], s[90:91], 1, v[50:51]
	v_lshlrev_b64 v[2:3], 4, v[2:3]
	v_lshlrev_b64 v[18:19], 4, v[18:19]
	v_lshlrev_b64 v[34:35], 4, v[34:35]
	v_lshlrev_b64 v[50:51], 4, v[50:51]
	v_lshl_add_u64 v[10:11], s[16:17], 0, v[2:3]
	v_lshl_add_u64 v[26:27], s[16:17], 0, v[18:19]
	v_lshl_add_u64 v[42:43], s[16:17], 0, v[34:35]
	v_lshl_add_u64 v[58:59], s[16:17], 0, v[50:51]
	s_mov_b64 s[100:101], 0x10000
	global_load_dwordx4 v[14:17], v[10:11], off offset:16
	v_lshl_add_u64 v[2:3], v[10:11], 0, s[100:101]
	global_load_dwordx4 v[10:13], v[10:11], off
	global_load_dwordx4 v[6:9], v[2:3], off offset:16
	s_nop 0
	global_load_dwordx4 v[2:5], v[2:3], off
	global_load_dwordx4 v[30:33], v[26:27], off offset:16
	v_lshl_add_u64 v[18:19], v[26:27], 0, s[100:101]
	global_load_dwordx4 v[26:29], v[26:27], off
	global_load_dwordx4 v[22:25], v[18:19], off offset:16
	s_nop 0
	global_load_dwordx4 v[18:21], v[18:19], off
	global_load_dwordx4 v[46:49], v[42:43], off offset:16
	v_lshl_add_u64 v[34:35], v[42:43], 0, s[100:101]
	global_load_dwordx4 v[42:45], v[42:43], off
	global_load_dwordx4 v[38:41], v[34:35], off offset:16
	s_nop 0
	global_load_dwordx4 v[34:37], v[34:35], off
	global_load_dwordx4 v[62:65], v[58:59], off offset:16
	v_lshl_add_u64 v[50:51], v[58:59], 0, s[100:101]
	global_load_dwordx4 v[58:61], v[58:59], off
	global_load_dwordx4 v[54:57], v[50:51], off offset:16
	s_nop 0
	global_load_dwordx4 v[50:53], v[50:51], off
	v_bfe_i32 v76, v178, 5, 26
	v_lshlrev_b32_e32 v77, 7, v76
	v_xor_b32_e32 v76, v76, v68
	v_lshlrev_b32_e32 v69, 2, v178
	v_lshlrev_b32_e32 v76, 5, v76
	v_lshlrev_b32_e32 v67, 1, v178
	v_and_b32_e32 v69, 28, v69
	v_and_b32_e32 v76, 0x60, v76
	v_or3_b32 v181, v76, v77, v69
	v_add_u32_e32 v76, 0x400, v67
	v_ashrrev_i32_e32 v76, 6, v76
	v_lshlrev_b32_e32 v77, 7, v76
	v_xor_b32_e32 v76, v76, v68
	v_lshlrev_b32_e32 v76, 5, v76
	v_and_b32_e32 v76, 0x60, v76
	v_or3_b32 v182, v76, v77, v69
	v_add_u32_e32 v76, 0x800, v67
	v_ashrrev_i32_e32 v76, 6, v76
	v_lshlrev_b32_e32 v77, 7, v76
	v_xor_b32_e32 v76, v76, v68
	v_lshlrev_b32_e32 v76, 5, v76
	v_add_u32_e32 v67, 0xc00, v67
	v_and_b32_e32 v76, 0x60, v76
	v_ashrrev_i32_e32 v67, 6, v67
	s_ashr_i32 s0, s0, 6
	v_or3_b32 v183, v76, v77, v69
	v_lshlrev_b32_e32 v76, 7, v67
	v_xor_b32_e32 v67, v67, v68
	s_lshl_b32 s1, s0, 14
	v_lshlrev_b32_e32 v73, 3, v178
	v_lshlrev_b32_e32 v67, 5, v67
	s_add_i32 s1, s1, 0
	v_lshrrev_b32_e32 v70, 4, v178
	v_bfe_u32 v71, v178, 4, 1
	v_bfe_u32 v72, v178, 2, 2
	v_and_b32_e32 v73, 24, v73
	v_and_b32_e32 v67, 0x60, v67
	v_bfe_u32 v66, v178, 5, 1
	v_add_u32_e32 v73, s1, v73
	v_lshlrev_b32_e32 v74, 7, v178
	v_and_b32_e32 v75, 15, v178
	v_or3_b32 v184, v67, v76, v69
	v_bitop3_b32 v67, v70, v72, 1 bitop3:0x6c
	v_lshlrev_b32_e32 v68, 7, v72
	v_bitop3_b32 v69, v71, v72, 2 bitop3:0x36
	v_and_b32_e32 v74, 0xf80, v74
	v_lshl_add_u32 v67, v67, 5, v73
	v_lshl_or_b32 v68, v66, 9, v68
	v_lshl_add_u32 v69, v69, 5, v73
	v_bitop3_b32 v70, v66, v178, 15 bitop3:0x78
	v_bitop3_b32 v71, v66, v75, 2 bitop3:0x36
	v_bitop3_b32 v72, v66, v75, 4 bitop3:0x36
	v_bitop3_b32 v73, v66, v75, 6 bitop3:0x36
	v_bitop3_b32 v76, v66, v75, 8 bitop3:0x36
	v_bitop3_b32 v77, v66, v75, 10 bitop3:0x36
	v_bitop3_b32 v78, v66, v75, 12 bitop3:0x36
	v_bitop3_b32 v66, v66, v75, 14 bitop3:0x36
	v_and_b32_e32 v179, 63, v178
	s_ashr_i32 s5, s4, 31
	v_readlane_b32 s6, v254, 50
	v_add_u32_e32 v74, s1, v74
	s_lshl_b32 s9, s0, 1
	v_lshlrev_b32_e32 v70, 3, v70
	v_lshlrev_b32_e32 v71, 3, v71
	v_lshlrev_b32_e32 v72, 3, v72
	v_lshlrev_b32_e32 v73, 3, v73
	v_lshlrev_b32_e32 v76, 3, v76
	v_lshlrev_b32_e32 v77, 3, v77
	v_lshlrev_b32_e32 v78, 3, v78
	v_lshlrev_b32_e32 v66, 3, v66
	v_lshl_add_u32 v180, v179, 4, s6
	s_lshl_b32 s8, s0, 9
	s_or_b32 s12, s9, 1
	s_lshl_b64 s[34:35], s[4:5], 16
	v_add_u32_e32 v185, v67, v68
	v_add_u32_e32 v186, v69, v68
	v_add_u32_e32 v187, v74, v70
	v_add_u32_e32 v188, v74, v71
	v_add_u32_e32 v189, v74, v72
	v_add_u32_e32 v190, v74, v73
	v_add_u32_e32 v191, v74, v76
	v_add_u32_e32 v192, v74, v77
	v_add_u32_e32 v193, v74, v78
	v_add_u32_e32 v194, v74, v66
	s_mov_b64 s[66:67], s[94:95]
	s_mov_b32 s0, s2
; #define LAS __attribute__((address_space(3)))
; __device__ void fft_phase(const Args& a, LAS unsigned char* lds) {
;     ...
;     __syncthreads();
; #pragma unroll
;     for (int it = 0; it < 4; ++it) {
;         const int token = 2 * (tid + NTHREADS * it);
;         const int n1 = token >> 6, n2 = token & 63;
;         const int off = n1 * 128 + (((n2 >> 4) ^ (n1 & 3)) << 5) + (n2 & 15) * 2;
; #pragma unroll
;         for (int ch = 0; ch < 8; ++ch) {
;             *(LAS f16x2*)(lds + ch * 16384 + off) = (f16x2){pin[it][0][ch], pin[it][2][ch]};
;             *(LAS f16x2*)(lds + ch * 16384 + 8192 + off) = (f16x2){pin[it][1][ch], pin[it][3][ch]};
;         }
;     }
;     __syncthreads();
.LBB0_392:
	s_waitcnt vmcnt(0)
	v_perm_b32 v66, v62, v58, s48
	v_add_u32_e32 v67, 0, v181
	v_perm_b32 v68, v54, v50, s48
	v_perm_b32 v58, v62, v58, s49
	v_perm_b32 v50, v54, v50, s49
	s_barrier
	ds_write2st64_b32 v67, v58, v50 offset0:64 offset1:96
	v_perm_b32 v50, v63, v59, s48
	v_perm_b32 v54, v55, v51, s48
	ds_write2st64_b32 v67, v50, v54 offset0:128 offset1:160
	v_perm_b32 v50, v63, v59, s49
	v_perm_b32 v51, v55, v51, s49
	s_add_i32 s1, 0, 0x10000
	ds_write2st64_b32 v67, v50, v51 offset0:192 offset1:224
	v_perm_b32 v50, v64, v60, s48
	v_add_u32_e32 v51, s1, v181
	s_add_i32 s5, 0, 0x12000
	ds_write_b32 v51, v50
	v_perm_b32 v50, v56, v52, s48
	v_add_u32_e32 v51, s5, v181
	s_add_i32 s6, 0, 0x14000
	ds_write_b32 v51, v50
	v_perm_b32 v50, v64, v60, s49
	v_add_u32_e32 v51, s6, v181
	s_add_i32 s7, 0, 0x16000
	ds_write_b32 v51, v50
	v_perm_b32 v50, v56, v52, s49
	v_add_u32_e32 v51, s7, v181
	s_add_i32 s13, 0, 0x18000
	ds_write_b32 v51, v50
	v_perm_b32 v50, v65, v61, s48
	v_add_u32_e32 v51, s13, v181
	s_add_i32 s14, 0, 0x1a000
	ds_write_b32 v51, v50
	v_perm_b32 v50, v57, v53, s48
	v_add_u32_e32 v51, s14, v181
	s_add_i32 s15, 0, 0x1c000
	ds_write_b32 v51, v50
	v_perm_b32 v50, v65, v61, s49
	v_add_u32_e32 v51, s15, v181
	s_add_i32 s31, 0, 0x1e000
	ds_write_b32 v51, v50
	v_perm_b32 v50, v57, v53, s49
	v_add_u32_e32 v51, s31, v181
	ds_write_b32 v51, v50
	v_perm_b32 v50, v46, v42, s48
	v_add_u32_e32 v51, 0, v182
	v_perm_b32 v52, v38, v34, s48
	v_perm_b32 v42, v46, v42, s49
	v_perm_b32 v34, v38, v34, s49
	ds_write2st64_b32 v67, v66, v68 offset1:32
	ds_write2st64_b32 v51, v42, v34 offset0:64 offset1:96
	v_perm_b32 v34, v47, v43, s48
	v_perm_b32 v38, v39, v35, s48
	ds_write2st64_b32 v51, v34, v38 offset0:128 offset1:160
	v_perm_b32 v34, v47, v43, s49
	v_perm_b32 v35, v39, v35, s49
	ds_write2st64_b32 v51, v34, v35 offset0:192 offset1:224
	v_perm_b32 v34, v48, v44, s48
	v_add_u32_e32 v35, s1, v182
	ds_write_b32 v35, v34
	v_perm_b32 v34, v40, v36, s48
	v_add_u32_e32 v35, s5, v182
	ds_write_b32 v35, v34
	v_perm_b32 v34, v48, v44, s49
	v_add_u32_e32 v35, s6, v182
	ds_write_b32 v35, v34
	v_perm_b32 v34, v40, v36, s49
	v_add_u32_e32 v35, s7, v182
	ds_write_b32 v35, v34
	v_perm_b32 v34, v49, v45, s48
	v_add_u32_e32 v35, s13, v182
	ds_write_b32 v35, v34
	v_perm_b32 v34, v41, v37, s48
	v_add_u32_e32 v35, s14, v182
	ds_write_b32 v35, v34
	v_perm_b32 v34, v49, v45, s49
	v_add_u32_e32 v35, s15, v182
	ds_write_b32 v35, v34
	v_perm_b32 v34, v41, v37, s49
	v_add_u32_e32 v35, s31, v182
	ds_write_b32 v35, v34
	v_perm_b32 v34, v30, v26, s48
	v_add_u32_e32 v35, 0, v183
	v_perm_b32 v36, v22, v18, s48
	v_perm_b32 v26, v30, v26, s49
	v_perm_b32 v18, v22, v18, s49
	ds_write2st64_b32 v51, v50, v52 offset1:32
	ds_write2st64_b32 v35, v26, v18 offset0:64 offset1:96
	v_perm_b32 v18, v31, v27, s48
	v_perm_b32 v22, v23, v19, s48
	ds_write2st64_b32 v35, v18, v22 offset0:128 offset1:160
	v_perm_b32 v18, v31, v27, s49
	v_perm_b32 v19, v23, v19, s49
	ds_write2st64_b32 v35, v18, v19 offset0:192 offset1:224
	v_perm_b32 v18, v32, v28, s48
	v_add_u32_e32 v19, s1, v183
	ds_write_b32 v19, v18
	v_perm_b32 v18, v24, v20, s48
	v_add_u32_e32 v19, s5, v183
	ds_write_b32 v19, v18
	v_perm_b32 v18, v32, v28, s49
	v_add_u32_e32 v19, s6, v183
	ds_write_b32 v19, v18
	v_perm_b32 v18, v24, v20, s49
	v_add_u32_e32 v19, s7, v183
	ds_write_b32 v19, v18
	v_perm_b32 v18, v33, v29, s48
	v_add_u32_e32 v19, s13, v183
	ds_write_b32 v19, v18
	v_perm_b32 v18, v25, v21, s48
	v_add_u32_e32 v19, s14, v183
	ds_write_b32 v19, v18
	v_perm_b32 v18, v33, v29, s49
	v_add_u32_e32 v19, s15, v183
	ds_write_b32 v19, v18
	v_perm_b32 v18, v25, v21, s49
	v_add_u32_e32 v19, s31, v183
	ds_write_b32 v19, v18
	v_perm_b32 v18, v14, v10, s48
	v_add_u32_e32 v19, 0, v184
	v_perm_b32 v20, v6, v2, s48
	v_perm_b32 v10, v14, v10, s49
	v_perm_b32 v2, v6, v2, s49
	ds_write2st64_b32 v35, v34, v36 offset1:32
	ds_write2st64_b32 v19, v10, v2 offset0:64 offset1:96
	v_perm_b32 v2, v15, v11, s48
	v_perm_b32 v6, v7, v3, s48
	ds_write2st64_b32 v19, v2, v6 offset0:128 offset1:160
	v_perm_b32 v2, v15, v11, s49
	v_perm_b32 v3, v7, v3, s49
	ds_write2st64_b32 v19, v2, v3 offset0:192 offset1:224
	v_perm_b32 v2, v16, v12, s48
	v_add_u32_e32 v3, s1, v184
	ds_write_b32 v3, v2
	v_perm_b32 v2, v8, v4, s48
	v_add_u32_e32 v3, s5, v184
	ds_write_b32 v3, v2
	v_perm_b32 v2, v16, v12, s49
	v_add_u32_e32 v3, s6, v184
	ds_write_b32 v3, v2
	v_perm_b32 v2, v8, v4, s49
	v_add_u32_e32 v3, s7, v184
	ds_write_b32 v3, v2
	v_perm_b32 v2, v17, v13, s48
	v_add_u32_e32 v3, s13, v184
	ds_write_b32 v3, v2
	v_perm_b32 v2, v9, v5, s48
	v_add_u32_e32 v3, s14, v184
	ds_write_b32 v3, v2
	v_perm_b32 v2, v17, v13, s49
	v_add_u32_e32 v3, s15, v184
	ds_write_b32 v3, v2
	v_perm_b32 v2, v9, v5, s49
	v_add_u32_e32 v3, s31, v184
	ds_write2st64_b32 v19, v18, v20 offset1:32
	ds_write_b32 v3, v2
	s_waitcnt lgkmcnt(0)
	s_barrier
; #define LAS __attribute__((address_space(3)))
; __device__ void fft_phase(const Args& a, LAS unsigned char* lds) {
;     ...
;     for (int mt = 0; mt < 2; ++mt) {
;         f32x16 Yr[2], Yi[2];
; #pragma unroll
;         for (int j = 0; j < 2; ++j)
; #pragma unroll
;             for (int e = 0; e < 16; ++e) { Yr[j][e] = 0.f; Yi[j][e] = 0.f; }
; #pragma unroll
;         for (int which = 0; which < 2; ++which)
; #pragma unroll
;             for (int s = 0; s < 4; ++s) {
;                 LAS unsigned char* pa = img + which * 8192 + (16 * s + 4 * h + tq) * 128 + (((2 * mt + blk) ^ tq) << 5) + tp * 8;
;                 const f16x8 af = tr_pair(pa, pa + 8 * 128);
; #pragma unroll
;                 for (int kt = 0; kt < 2; ++kt) {
;                     const f16x8 cf = CF[(s * 2 + kt) * 64], sf = which ? NSF[(s * 2 + kt) * 64] : SF[(s * 2 + kt) * 64];
;                     if (which == 0) { Yr[kt] = __builtin_amdgcn_mfma_f32_32x32x16_f16(af, cf, Yr[kt], 0, 0, 0); Yi[kt] = __builtin_amdgcn_mfma_f32_32x32x16_f16(af, sf, Yi[kt], 0, 0, 0); }
;                     else { Yr[kt] = __builtin_amdgcn_mfma_f32_32x32x16_f16(af, sf, Yr[kt], 0, 0, 0); Yi[kt] = __builtin_amdgcn_mfma_f32_32x32x16_f16(af, cf, Yi[kt], 0, 0, 0); }
;                 }
;             }
;         f16x8 trf[2][2], tif[2][2];
; #pragma unroll
;         for (int kt = 0; kt < 2; ++kt) {
;             int lane_l = lane; asm volatile("" : "+v"(lane_l));
;             const f32x4* tw = (const f32x4*)TW + ((mt * 2 + kt) * 8) * 64 + lane_l;
;             f32x16 tr, ti;
; #pragma unroll
;             for (int p = 0; p < 8; ++p) { const f32x4 cs = tw[p * 64];
;                 tr[2 * p] = Yr[kt][2 * p] * cs[0] - Yi[kt][2 * p] * cs[1]; ti[2 * p] = Yr[kt][2 * p] * cs[1] + Yi[kt][2 * p] * cs[0];
;                 tr[2 * p + 1] = Yr[kt][2 * p + 1] * cs[2] - Yi[kt][2 * p + 1] * cs[3]; ti[2 * p + 1] = Yr[kt][2 * p + 1] * cs[3] + Yi[kt][2 * p + 1] * cs[2]; }
	ds_read_b64_tr_b16 v[18:19], v185
	ds_read_b64_tr_b16 v[20:21], v185 offset:1024
	ds_read_b128 v[66:69], v180
	ds_read_b128 v[2:5], v180 offset:8192
	s_waitcnt lgkmcnt(0)
	v_mfma_f32_32x32x16_f16 v[50:65], v[18:21], v[2:5], 0
	ds_read_b128 v[70:73], v180 offset:1024
	ds_read_b128 v[22:25], v180 offset:9216
	ds_read_b64_tr_b16 v[74:75], v185 offset:2048
	ds_read_b64_tr_b16 v[76:77], v185 offset:3072
	ds_read_b128 v[78:81], v180 offset:2048
	ds_read_b128 v[82:85], v180 offset:10240
	s_mov_b32 s1, 0xf1001000
	s_add_i32 s5, s0, s4
	s_cmpk_lt_i32 s5, 0x300
	s_cselect_b64 s[6:7], -1, 0
	v_mfma_f32_32x32x16_f16 v[34:49], v[18:21], v[66:69], 0
	s_waitcnt lgkmcnt(5)
	v_mfma_f32_32x32x16_f16 v[2:17], v[18:21], v[70:73], 0
	s_waitcnt lgkmcnt(4)
	v_mfma_f32_32x32x16_f16 v[18:33], v[18:21], v[22:25], 0
	s_waitcnt lgkmcnt(0)
	v_mfma_f32_32x32x16_f16 v[50:65], v[74:77], v[82:85], v[50:65]
	ds_read_b128 v[82:85], v180 offset:3072
	ds_read_b128 v[86:89], v180 offset:11264
	v_mfma_f32_32x32x16_f16 v[34:49], v[74:77], v[78:81], v[34:49]
	s_waitcnt lgkmcnt(1)
	v_mfma_f32_32x32x16_f16 v[2:17], v[74:77], v[82:85], v[2:17]
	s_waitcnt lgkmcnt(0)
	v_mfma_f32_32x32x16_f16 v[18:33], v[74:77], v[86:89], v[18:33]
	ds_read_b64_tr_b16 v[74:75], v185 offset:4096
	ds_read_b64_tr_b16 v[76:77], v185 offset:5120
	ds_read_b128 v[86:89], v180 offset:4096
	ds_read_b128 v[90:93], v180 offset:12288
	s_waitcnt lgkmcnt(0)
	v_mfma_f32_32x32x16_f16 v[50:65], v[74:77], v[90:93], v[50:65]
	ds_read_b128 v[90:93], v180 offset:5120
	ds_read_b128 v[94:97], v180 offset:13312
	v_mfma_f32_32x32x16_f16 v[34:49], v[74:77], v[86:89], v[34:49]
	s_waitcnt lgkmcnt(1)
	v_mfma_f32_32x32x16_f16 v[2:17], v[74:77], v[90:93], v[2:17]
	s_waitcnt lgkmcnt(0)
	v_mfma_f32_32x32x16_f16 v[18:33], v[74:77], v[94:97], v[18:33]
	ds_read_b64_tr_b16 v[74:75], v185 offset:6144
	ds_read_b64_tr_b16 v[76:77], v185 offset:7168
	ds_read_b128 v[94:97], v180 offset:6144
	ds_read_b128 v[98:101], v180 offset:14336
	s_waitcnt lgkmcnt(0)
	v_mfma_f32_32x32x16_f16 v[50:65], v[74:77], v[98:101], v[50:65]
	ds_read_b128 v[98:101], v180 offset:7168
	ds_read_b128 v[102:105], v180 offset:15360
	v_mfma_f32_32x32x16_f16 v[34:49], v[74:77], v[94:97], v[34:49]
	s_waitcnt lgkmcnt(1)
	v_mfma_f32_32x32x16_f16 v[2:17], v[74:77], v[98:101], v[2:17]
	s_waitcnt lgkmcnt(0)
	v_mfma_f32_32x32x16_f16 v[18:33], v[74:77], v[102:105], v[18:33]
	ds_read_b64_tr_b16 v[74:75], v185 offset:8192
	ds_read_b64_tr_b16 v[76:77], v185 offset:9216
	ds_read_b128 v[102:105], v180 offset:16384
	s_waitcnt lgkmcnt(1)
	v_mfma_f32_32x32x16_f16 v[50:65], v[74:77], v[66:69], v[50:65]
	ds_read_b128 v[66:69], v180 offset:17408
	s_waitcnt lgkmcnt(1)
	v_mfma_f32_32x32x16_f16 v[34:49], v[74:77], v[102:105], v[34:49]
	s_waitcnt lgkmcnt(0)
	v_mfma_f32_32x32x16_f16 v[2:17], v[74:77], v[66:69], v[2:17]
	v_mfma_f32_32x32x16_f16 v[18:33], v[74:77], v[70:73], v[18:33]
	ds_read_b64_tr_b16 v[66:67], v185 offset:10240
	ds_read_b64_tr_b16 v[68:69], v185 offset:11264
	ds_read_b128 v[70:73], v180 offset:18432
	s_waitcnt lgkmcnt(0)
	v_mfma_f32_32x32x16_f16 v[34:49], v[66:69], v[70:73], v[34:49]
	ds_read_b128 v[70:73], v180 offset:19456
	v_mfma_f32_32x32x16_f16 v[50:65], v[66:69], v[78:81], v[50:65]
	s_waitcnt lgkmcnt(0)
	v_mfma_f32_32x32x16_f16 v[2:17], v[66:69], v[70:73], v[2:17]
	v_mfma_f32_32x32x16_f16 v[18:33], v[66:69], v[82:85], v[18:33]
	ds_read_b64_tr_b16 v[66:67], v185 offset:12288
	ds_read_b64_tr_b16 v[68:69], v185 offset:13312
	ds_read_b128 v[70:73], v180 offset:20480
	s_waitcnt lgkmcnt(0)
	v_mfma_f32_32x32x16_f16 v[34:49], v[66:69], v[70:73], v[34:49]
	ds_read_b128 v[70:73], v180 offset:21504
	v_mfma_f32_32x32x16_f16 v[50:65], v[66:69], v[86:89], v[50:65]
	s_waitcnt lgkmcnt(0)
	v_mfma_f32_32x32x16_f16 v[2:17], v[66:69], v[70:73], v[2:17]
	v_mfma_f32_32x32x16_f16 v[18:33], v[66:69], v[90:93], v[18:33]
	ds_read_b64_tr_b16 v[66:67], v185 offset:14336
	ds_read_b64_tr_b16 v[68:69], v185 offset:15360
	ds_read_b128 v[70:73], v180 offset:22528
	s_waitcnt lgkmcnt(0)
	v_mfma_f32_32x32x16_f16 v[34:49], v[66:69], v[70:73], v[34:49]
	ds_read_b128 v[70:73], v180 offset:23552
	v_mfma_f32_32x32x16_f16 v[50:65], v[66:69], v[94:97], v[50:65]
	s_waitcnt lgkmcnt(0)
	v_mfma_f32_32x32x16_f16 v[2:17], v[66:69], v[70:73], v[2:17]
	v_mfma_f32_32x32x16_f16 v[18:33], v[66:69], v[98:101], v[18:33]
	v_mov_b32_e32 v66, v179
	s_nop 0
	v_ashrrev_i32_e32 v67, 31, v66
	v_lshl_add_u64 v[66:67], v[66:67], 4, s[50:51]
	global_load_dwordx4 v[68:71], v[66:67], off
	global_load_dwordx4 v[72:75], v[66:67], off offset:1024
	global_load_dwordx4 v[76:79], v[66:67], off offset:2048
	global_load_dwordx4 v[80:83], v[66:67], off offset:3072
	v_add_co_u32_e32 v66, vcc, s47, v66
	s_waitcnt vmcnt(3)
	v_mov_b32_e32 v100, v68
	v_addc_co_u32_e32 v67, vcc, 0, v67, vcc
	global_load_dwordx4 v[84:87], v[66:67], off
	global_load_dwordx4 v[88:91], v[66:67], off offset:1024
	global_load_dwordx4 v[92:95], v[66:67], off offset:2048
	global_load_dwordx4 v[96:99], v[66:67], off offset:3072
	v_mov_b32_e32 v101, v70
	v_mov_b32_e32 v70, v69
	v_pk_mul_f32 v[66:67], v[50:51], v[70:71]
	s_waitcnt vmcnt(6)
	v_mov_b32_e32 v102, v72
	v_mov_b32_e32 v103, v74
	v_mov_b32_e32 v74, v73
	v_pk_mul_f32 v[50:51], v[50:51], v[100:101]
	v_pk_fma_f32 v[66:67], v[34:35], v[100:101], v[66:67] neg_lo:[0,0,1] neg_hi:[0,0,1]
	v_pk_mul_f32 v[68:69], v[52:53], v[74:75]
	v_pk_fma_f32 v[34:35], v[34:35], v[70:71], v[50:51]
	v_pk_mul_f32 v[50:51], v[52:53], v[102:103]
	v_pk_fma_f32 v[68:69], v[36:37], v[102:103], v[68:69] neg_lo:[0,0,1] neg_hi:[0,0,1]
	s_waitcnt vmcnt(5)
; __device__ void fft_phase(const Args& a, LAS unsigned char* lds) {
;     ...
;         f16x8 trf[2][2], tif[2][2];
; #pragma unroll
;         for (int kt = 0; kt < 2; ++kt) {
;             int lane_l = lane; asm volatile("" : "+v"(lane_l));
;             const f32x4* tw = (const f32x4*)TW + ((mt * 2 + kt) * 8) * 64 + lane_l;
;             f32x16 tr, ti;
; #pragma unroll
;             for (int p = 0; p < 8; ++p) { const f32x4 cs = tw[p * 64];
;                 tr[2 * p] = Yr[kt][2 * p] * cs[0] - Yi[kt][2 * p] * cs[1]; ti[2 * p] = Yr[kt][2 * p] * cs[1] + Yi[kt][2 * p] * cs[0];
;                 tr[2 * p + 1] = Yr[kt][2 * p + 1] * cs[2] - Yi[kt][2 * p + 1] * cs[3]; ti[2 * p + 1] = Yr[kt][2 * p + 1] * cs[3] + Yi[kt][2 * p + 1] * cs[2]; }
; #pragma unroll
;             for (int sp = 0; sp < 2; ++sp) { trf[kt][sp] = pack_p(tr, sp); tif[kt][sp] = pack_p(ti, sp); }
;         }
	v_mov_b32_e32 v72, v76
	v_mov_b32_e32 v73, v78
	v_mov_b32_e32 v78, v77
	v_pk_fma_f32 v[36:37], v[36:37], v[74:75], v[50:51]
	v_cvt_pk_f16_f32 v66, v66, v67
	v_cvt_pk_f16_f32 v67, v68, v69
	v_pk_mul_f32 v[68:69], v[54:55], v[78:79]
	s_waitcnt vmcnt(4)
	v_mov_b32_e32 v76, v80
	v_mov_b32_e32 v77, v82
	v_cvt_pk_f16_f32 v34, v34, v35
	v_cvt_pk_f16_f32 v35, v36, v37
	v_pk_mul_f32 v[36:37], v[54:55], v[72:73]
	v_pk_fma_f32 v[68:69], v[38:39], v[72:73], v[68:69] neg_lo:[0,0,1] neg_hi:[0,0,1]
	v_mov_b32_e32 v82, v81
	v_pk_fma_f32 v[36:37], v[38:39], v[78:79], v[36:37]
	v_pk_mul_f32 v[38:39], v[56:57], v[76:77]
	v_pk_mul_f32 v[80:81], v[56:57], v[82:83]
	v_pk_fma_f32 v[38:39], v[40:41], v[82:83], v[38:39]
	v_cvt_pk_f16_f32 v36, v36, v37
	v_cvt_pk_f16_f32 v37, v38, v39
	v_pk_fma_f32 v[80:81], v[40:41], v[76:77], v[80:81] neg_lo:[0,0,1] neg_hi:[0,0,1]
	v_cvt_pk_f16_f32 v68, v68, v69
	v_cvt_pk_f16_f32 v69, v80, v81
	s_waitcnt vmcnt(3)
	v_mov_b32_e32 v39, v86
	v_mov_b32_e32 v86, v85
	v_mov_b32_e32 v38, v84
	v_pk_mul_f32 v[40:41], v[58:59], v[86:87]
	s_nop 0
	v_pk_fma_f32 v[40:41], v[42:43], v[38:39], v[40:41] neg_lo:[0,0,1] neg_hi:[0,0,1]
	v_pk_mul_f32 v[38:39], v[58:59], v[38:39]
	v_cvt_pk_f16_f32 v70, v40, v41
	s_waitcnt vmcnt(2)
	v_mov_b32_e32 v41, v90
	v_mov_b32_e32 v90, v89
	v_mov_b32_e32 v40, v88
	v_pk_mul_f32 v[50:51], v[60:61], v[90:91]
	v_pk_fma_f32 v[38:39], v[42:43], v[86:87], v[38:39]
	v_pk_fma_f32 v[50:51], v[44:45], v[40:41], v[50:51] neg_lo:[0,0,1] neg_hi:[0,0,1]
	v_cvt_pk_f16_f32 v74, v38, v39
	v_cvt_pk_f16_f32 v71, v50, v51
	s_waitcnt vmcnt(1)
	v_mov_b32_e32 v51, v94
	v_mov_b32_e32 v94, v93
	v_pk_mul_f32 v[38:39], v[60:61], v[40:41]
	v_mov_b32_e32 v50, v92
	v_pk_mul_f32 v[52:53], v[62:63], v[94:95]
	v_pk_fma_f32 v[38:39], v[44:45], v[90:91], v[38:39]
	v_pk_fma_f32 v[52:53], v[46:47], v[50:51], v[52:53] neg_lo:[0,0,1] neg_hi:[0,0,1]
	v_cvt_pk_f16_f32 v75, v38, v39
	v_pk_mul_f32 v[38:39], v[62:63], v[50:51]
	v_cvt_pk_f16_f32 v72, v52, v53
	s_waitcnt vmcnt(0)
	v_mov_b32_e32 v52, v96
	v_mov_b32_e32 v53, v98
	v_pk_fma_f32 v[38:39], v[46:47], v[94:95], v[38:39]
	v_mov_b32_e32 v98, v97
	v_cvt_pk_f16_f32 v76, v38, v39
	v_pk_mul_f32 v[38:39], v[64:65], v[52:53]
	v_pk_mul_f32 v[54:55], v[64:65], v[98:99]
	v_pk_fma_f32 v[38:39], v[48:49], v[98:99], v[38:39]
	v_pk_fma_f32 v[54:55], v[48:49], v[52:53], v[54:55] neg_lo:[0,0,1] neg_hi:[0,0,1]
	v_cvt_pk_f16_f32 v77, v38, v39
	v_mov_b32_e32 v38, v179
	v_cvt_pk_f16_f32 v73, v54, v55
	v_ashrrev_i32_e32 v39, 31, v38
	v_lshl_add_u64 v[38:39], v[38:39], 4, s[54:55]
	global_load_dwordx4 v[40:43], v[38:39], off
	global_load_dwordx4 v[44:47], v[38:39], off offset:1024
	global_load_dwordx4 v[48:51], v[38:39], off offset:2048
	global_load_dwordx4 v[52:55], v[38:39], off offset:3072
	v_add_co_u32_e32 v38, vcc, s47, v38
	s_waitcnt vmcnt(3)
	v_mov_b32_e32 v64, v40
	v_addc_co_u32_e32 v39, vcc, 0, v39, vcc
	global_load_dwordx4 v[56:59], v[38:39], off
	global_load_dwordx4 v[60:63], v[38:39], off offset:1024
	global_load_dwordx4 v[86:89], v[38:39], off offset:2048
	global_load_dwordx4 v[90:93], v[38:39], off offset:3072
	v_mov_b32_e32 v65, v42
	v_mov_b32_e32 v42, v41
	v_pk_mul_f32 v[38:39], v[18:19], v[42:43]
	v_pk_mul_f32 v[18:19], v[18:19], v[64:65]
	v_pk_fma_f32 v[38:39], v[2:3], v[64:65], v[38:39] neg_lo:[0,0,1] neg_hi:[0,0,1]
	s_waitcnt vmcnt(6)
	v_mov_b32_e32 v80, v44
	v_mov_b32_e32 v81, v46
	v_pk_fma_f32 v[2:3], v[2:3], v[42:43], v[18:19]
	v_mov_b32_e32 v46, v45
	v_cvt_pk_f16_f32 v78, v2, v3
	v_pk_mul_f32 v[2:3], v[20:21], v[80:81]
	s_waitcnt vmcnt(5)
	v_mov_b32_e32 v44, v48
	v_mov_b32_e32 v45, v50
	v_pk_fma_f32 v[2:3], v[4:5], v[46:47], v[2:3]
	v_mov_b32_e32 v50, v49
	v_cvt_pk_f16_f32 v79, v2, v3
	v_pk_mul_f32 v[2:3], v[22:23], v[44:45]
	v_pk_mul_f32 v[40:41], v[20:21], v[46:47]
	s_waitcnt vmcnt(4)
	v_mov_b32_e32 v48, v52
	v_mov_b32_e32 v49, v54
	v_pk_fma_f32 v[2:3], v[6:7], v[50:51], v[2:3]
	v_pk_fma_f32 v[40:41], v[4:5], v[80:81], v[40:41] neg_lo:[0,0,1] neg_hi:[0,0,1]
	v_mov_b32_e32 v54, v53
	v_cvt_pk_f16_f32 v80, v2, v3
	v_pk_mul_f32 v[2:3], v[24:25], v[48:49]
	v_cvt_pk_f16_f32 v38, v38, v39
	v_pk_fma_f32 v[2:3], v[8:9], v[54:55], v[2:3]
	v_cvt_pk_f16_f32 v39, v40, v41
	v_cvt_pk_f16_f32 v81, v2, v3
	v_pk_mul_f32 v[40:41], v[22:23], v[50:51]
	v_pk_mul_f32 v[52:53], v[24:25], v[54:55]
	v_pk_fma_f32 v[40:41], v[6:7], v[44:45], v[40:41] neg_lo:[0,0,1] neg_hi:[0,0,1]
	v_pk_fma_f32 v[52:53], v[8:9], v[48:49], v[52:53] neg_lo:[0,0,1] neg_hi:[0,0,1]
	ds_read_b128 v[130:133], v180
	ds_read_b128 v[134:137], v180 offset:16384
	ds_read_b128 v[138:141], v180 offset:1024
	ds_read_b128 v[142:145], v180 offset:17408
	v_cvt_pk_f16_f32 v40, v40, v41
	v_cvt_pk_f16_f32 v41, v52, v53
	ds_read_b128 v[146:149], v180 offset:2048
	ds_read_b128 v[150:153], v180 offset:18432
	ds_read_b128 v[154:157], v180 offset:3072
	ds_read_b128 v[158:161], v180 offset:19456
	s_waitcnt vmcnt(3)
	v_mov_b32_e32 v3, v58
	v_mov_b32_e32 v58, v57
	v_mov_b32_e32 v2, v56
	v_pk_mul_f32 v[4:5], v[26:27], v[58:59]
	s_nop 0
	v_pk_fma_f32 v[4:5], v[10:11], v[2:3], v[4:5] neg_lo:[0,0,1] neg_hi:[0,0,1]
	v_pk_mul_f32 v[2:3], v[26:27], v[2:3]
	v_cvt_pk_f16_f32 v82, v4, v5
	s_waitcnt vmcnt(2)
	v_mov_b32_e32 v5, v62
	v_mov_b32_e32 v62, v61
	v_mov_b32_e32 v4, v60
	v_pk_mul_f32 v[6:7], v[28:29], v[62:63]
	v_pk_fma_f32 v[2:3], v[10:11], v[58:59], v[2:3]
	v_pk_fma_f32 v[6:7], v[12:13], v[4:5], v[6:7] neg_lo:[0,0,1] neg_hi:[0,0,1]
	s_nop 0
	v_cvt_pk_f16_f32 v83, v6, v7
	s_waitcnt vmcnt(1)
	v_mov_b32_e32 v7, v88
	v_mov_b32_e32 v88, v87
	v_mov_b32_e32 v6, v86
	v_pk_mul_f32 v[8:9], v[30:31], v[88:89]
	v_cvt_pk_f16_f32 v86, v2, v3
	v_pk_fma_f32 v[8:9], v[14:15], v[6:7], v[8:9] neg_lo:[0,0,1] neg_hi:[0,0,1]
	v_pk_mul_f32 v[2:3], v[28:29], v[4:5]
	v_cvt_pk_f16_f32 v84, v8, v9
	s_waitcnt vmcnt(0)
; #define LAS __attribute__((address_space(3)))
; __device__ void fft_phase(const Args& a, LAS unsigned char* lds) {
;     ...
; #pragma unroll
;         for (int which = 0; which < 2; ++which)
; #pragma unroll
;             for (int s = 0; s < 4; ++s) {
;                 LAS unsigned char* pa = img + which * 8192 + (16 * s + 4 * h + tq) * 128 + (((2 * mt + blk) ^ tq) << 5) + tp * 8;
;                 const f16x8 af = tr_pair(pa, pa + 8 * 128);
; #pragma unroll
;                 for (int kt = 0; kt < 2; ++kt) {
;                     const f16x8 cf = CF[(s * 2 + kt) * 64], sf = which ? NSF[(s * 2 + kt) * 64] : SF[(s * 2 + kt) * 64];
;                     if (which == 0) { Yr[kt] = __builtin_amdgcn_mfma_f32_32x32x16_f16(af, cf, Yr[kt], 0, 0, 0); Yi[kt] = __builtin_amdgcn_mfma_f32_32x32x16_f16(af, sf, Yi[kt], 0, 0, 0); }
;                     else { Yr[kt] = __builtin_amdgcn_mfma_f32_32x32x16_f16(af, sf, Yr[kt], 0, 0, 0); Yi[kt] = __builtin_amdgcn_mfma_f32_32x32x16_f16(af, cf, Yi[kt], 0, 0, 0); }
;                 }
;             }
;     ...
; #pragma unroll
;         for (int sp = 0; sp < 2; ++sp)
; #pragma unroll
;             for (int mt2 = 0; mt2 < 2; ++mt2) {
;                 const f16x8 cf = CF[((2 * mt + sp) * 2 + mt2) * 64], nsf = NSF[((2 * mt + sp) * 2 + mt2) * 64];
; #pragma unroll
;                 for (int kt = 0; kt < 2; ++kt) {
;                     X[mt2][kt] = __builtin_amdgcn_mfma_f32_32x32x16_f16(cf, trf[kt][sp], X[mt2][kt], 0, 0, 0);
;                     X[mt2][kt] = __builtin_amdgcn_mfma_f32_32x32x16_f16(nsf, tif[kt][sp], X[mt2][kt], 0, 0, 0);
;                 }
;             }
	v_mov_b32_e32 v9, v92
	v_mov_b32_e32 v92, v91
	v_pk_fma_f32 v[2:3], v[12:13], v[62:63], v[2:3]
	v_mov_b32_e32 v8, v90
	v_pk_mul_f32 v[18:19], v[32:33], v[92:93]
	v_cvt_pk_f16_f32 v87, v2, v3
	v_pk_mul_f32 v[2:3], v[30:31], v[6:7]
	v_pk_fma_f32 v[18:19], v[16:17], v[8:9], v[18:19] neg_lo:[0,0,1] neg_hi:[0,0,1]
	v_pk_fma_f32 v[2:3], v[14:15], v[88:89], v[2:3]
	v_cvt_pk_f16_f32 v85, v18, v19
	v_cvt_pk_f16_f32 v88, v2, v3
	v_pk_mul_f32 v[2:3], v[32:33], v[8:9]
	s_waitcnt lgkmcnt(7)
	v_mfma_f32_32x32x16_f16 v[18:33], v[130:133], v[66:69], 0
	v_fma_f32 v2, v16, v92, v2
	v_fma_f32 v3, v17, v93, v3
	v_cvt_pk_f16_f32 v89, v2, v3
	s_waitcnt lgkmcnt(5)
	v_mfma_f32_32x32x16_f16 v[50:65], v[138:141], v[66:69], 0
	v_mfma_f32_32x32x16_f16 v[18:33], v[134:137], v[34:37], v[18:33]
	v_mfma_f32_32x32x16_f16 v[2:17], v[130:133], v[38:41], 0
	s_waitcnt lgkmcnt(4)
	v_mfma_f32_32x32x16_f16 v[50:65], v[142:145], v[34:37], v[50:65]
	v_mfma_f32_32x32x16_f16 v[34:49], v[138:141], v[38:41], 0
	v_mfma_f32_32x32x16_f16 v[2:17], v[134:137], v[78:81], v[2:17]
	v_mfma_f32_32x32x16_f16 v[34:49], v[142:145], v[78:81], v[34:49]
	s_waitcnt lgkmcnt(3)
	v_mfma_f32_32x32x16_f16 v[2:17], v[146:149], v[82:85], v[2:17]
	s_waitcnt lgkmcnt(1)
	v_mfma_f32_32x32x16_f16 v[34:49], v[154:157], v[82:85], v[34:49]
	ds_read_b64_tr_b16 v[82:83], v186
	ds_read_b64_tr_b16 v[84:85], v186 offset:1024
	ds_read_b128 v[66:69], v180 offset:8192
	v_mfma_f32_32x32x16_f16 v[18:33], v[146:149], v[70:73], v[18:33]
	v_mfma_f32_32x32x16_f16 v[50:65], v[154:157], v[70:73], v[50:65]
	v_mfma_f32_32x32x16_f16 v[2:17], v[150:153], v[86:89], v[2:17]
	s_waitcnt lgkmcnt(3)
	v_mfma_f32_32x32x16_f16 v[34:49], v[158:161], v[86:89], v[34:49]
	ds_read_b128 v[86:89], v180 offset:9216
	ds_read_b64_tr_b16 v[162:163], v186 offset:2048
	ds_read_b64_tr_b16 v[164:165], v186 offset:3072
	ds_read_b128 v[166:169], v180 offset:10240
	s_waitcnt lgkmcnt(4)
	v_mfma_f32_32x32x16_f16 v[114:129], v[82:85], v[66:69], 0
	v_mfma_f32_32x32x16_f16 v[18:33], v[150:153], v[74:77], v[18:33]
	v_mfma_f32_32x32x16_f16 v[50:65], v[158:161], v[74:77], v[50:65]
	v_mfma_f32_32x32x16_f16 v[98:113], v[82:85], v[130:133], 0
	v_mfma_f32_32x32x16_f16 v[66:81], v[82:85], v[138:141], 0
	s_waitcnt lgkmcnt(3)
	v_mfma_f32_32x32x16_f16 v[82:97], v[82:85], v[86:89], 0
	s_waitcnt lgkmcnt(0)
	v_mfma_f32_32x32x16_f16 v[114:129], v[162:165], v[166:169], v[114:129]
	ds_read_b128 v[166:169], v180 offset:11264
	v_mfma_f32_32x32x16_f16 v[98:113], v[162:165], v[146:149], v[98:113]
	v_mfma_f32_32x32x16_f16 v[66:81], v[162:165], v[154:157], v[66:81]
	s_waitcnt lgkmcnt(0)
	v_mfma_f32_32x32x16_f16 v[82:97], v[162:165], v[166:169], v[82:97]
	ds_read_b64_tr_b16 v[170:171], v186 offset:4096
	ds_read_b64_tr_b16 v[172:173], v186 offset:5120
	ds_read_b128 v[166:169], v180 offset:4096
	ds_read_b128 v[162:165], v180 offset:12288
	s_waitcnt lgkmcnt(0)
	v_mfma_f32_32x32x16_f16 v[114:129], v[170:173], v[162:165], v[114:129]
	ds_read_b128 v[162:165], v180 offset:5120
	ds_read_b128 v[174:177], v180 offset:13312
	v_mfma_f32_32x32x16_f16 v[98:113], v[170:173], v[166:169], v[98:113]
	s_waitcnt lgkmcnt(1)
	v_mfma_f32_32x32x16_f16 v[66:81], v[170:173], v[162:165], v[66:81]
	s_waitcnt lgkmcnt(0)
	v_mfma_f32_32x32x16_f16 v[82:97], v[170:173], v[174:177], v[82:97]
	ds_read_b64_tr_b16 v[200:201], v186 offset:6144
	ds_read_b64_tr_b16 v[202:203], v186 offset:7168
	ds_read_b128 v[170:173], v180 offset:6144
	ds_read_b128 v[174:177], v180 offset:14336
	s_waitcnt lgkmcnt(0)
	v_mfma_f32_32x32x16_f16 v[114:129], v[200:203], v[174:177], v[114:129]
	ds_read_b128 v[174:177], v180 offset:7168
	ds_read_b128 v[204:207], v180 offset:15360
	v_mfma_f32_32x32x16_f16 v[98:113], v[200:203], v[170:173], v[98:113]
	s_waitcnt lgkmcnt(1)
	v_mfma_f32_32x32x16_f16 v[66:81], v[200:203], v[174:177], v[66:81]
	s_waitcnt lgkmcnt(0)
	v_mfma_f32_32x32x16_f16 v[82:97], v[200:203], v[204:207], v[82:97]
	ds_read_b64_tr_b16 v[200:201], v186 offset:8192
	ds_read_b64_tr_b16 v[202:203], v186 offset:9216
	s_waitcnt lgkmcnt(0)
	v_mfma_f32_32x32x16_f16 v[98:113], v[200:203], v[134:137], v[98:113]
	v_mfma_f32_32x32x16_f16 v[114:129], v[200:203], v[130:133], v[114:129]
	ds_read_b64_tr_b16 v[130:131], v186 offset:10240
	ds_read_b64_tr_b16 v[132:133], v186 offset:11264
	v_mfma_f32_32x32x16_f16 v[66:81], v[200:203], v[142:145], v[66:81]
	v_mfma_f32_32x32x16_f16 v[82:97], v[200:203], v[138:141], v[82:97]
	s_waitcnt lgkmcnt(0)
	v_mfma_f32_32x32x16_f16 v[98:113], v[130:133], v[150:153], v[98:113]
	v_mfma_f32_32x32x16_f16 v[114:129], v[130:133], v[146:149], v[114:129]
	v_mfma_f32_32x32x16_f16 v[66:81], v[130:133], v[158:161], v[66:81]
	v_mfma_f32_32x32x16_f16 v[82:97], v[130:133], v[154:157], v[82:97]
	ds_read_b64_tr_b16 v[130:131], v186 offset:12288
	ds_read_b64_tr_b16 v[132:133], v186 offset:13312
	ds_read_b128 v[134:137], v180 offset:20480
	s_waitcnt lgkmcnt(0)
	v_mfma_f32_32x32x16_f16 v[98:113], v[130:133], v[134:137], v[98:113]
	ds_read_b128 v[134:137], v180 offset:21504
	v_mfma_f32_32x32x16_f16 v[114:129], v[130:133], v[166:169], v[114:129]
	s_waitcnt lgkmcnt(0)
	v_mfma_f32_32x32x16_f16 v[66:81], v[130:133], v[134:137], v[66:81]
	v_mfma_f32_32x32x16_f16 v[82:97], v[130:133], v[162:165], v[82:97]
	ds_read_b64_tr_b16 v[130:131], v186 offset:14336
	ds_read_b64_tr_b16 v[132:133], v186 offset:15360
	ds_read_b128 v[134:137], v180 offset:22528
	s_waitcnt lgkmcnt(0)
	v_mfma_f32_32x32x16_f16 v[98:113], v[130:133], v[134:137], v[98:113]
	ds_read_b128 v[134:137], v180 offset:23552
	v_mfma_f32_32x32x16_f16 v[114:129], v[130:133], v[170:173], v[114:129]
	s_waitcnt lgkmcnt(0)
; __device__ void fft_phase(const Args& a, LAS unsigned char* lds) {
;     ...
;         for (int kt = 0; kt < 2; ++kt) {
;             int lane_l = lane; asm volatile("" : "+v"(lane_l));
;             const f32x4* tw = (const f32x4*)TW + ((mt * 2 + kt) * 8) * 64 + lane_l;
;             f32x16 tr, ti;
; #pragma unroll
;             for (int p = 0; p < 8; ++p) { const f32x4 cs = tw[p * 64];
;                 tr[2 * p] = Yr[kt][2 * p] * cs[0] - Yi[kt][2 * p] * cs[1]; ti[2 * p] = Yr[kt][2 * p] * cs[1] + Yi[kt][2 * p] * cs[0];
;                 tr[2 * p + 1] = Yr[kt][2 * p + 1] * cs[2] - Yi[kt][2 * p + 1] * cs[3]; ti[2 * p + 1] = Yr[kt][2 * p + 1] * cs[3] + Yi[kt][2 * p + 1] * cs[2]; }
; #pragma unroll
;             for (int sp = 0; sp < 2; ++sp) { trf[kt][sp] = pack_p(tr, sp); tif[kt][sp] = pack_p(ti, sp); }
;         }
	v_mfma_f32_32x32x16_f16 v[66:81], v[130:133], v[134:137], v[66:81]
	v_mfma_f32_32x32x16_f16 v[82:97], v[130:133], v[174:177], v[82:97]
	v_mov_b32_e32 v130, v179
	s_nop 0
	v_ashrrev_i32_e32 v131, 31, v130
	v_lshl_add_u64 v[130:131], v[130:131], 4, s[56:57]
	global_load_dwordx4 v[132:135], v[130:131], off
	global_load_dwordx4 v[136:139], v[130:131], off offset:1024
	global_load_dwordx4 v[140:143], v[130:131], off offset:2048
	global_load_dwordx4 v[144:147], v[130:131], off offset:3072
	v_add_co_u32_e32 v130, vcc, s47, v130
	s_waitcnt vmcnt(3)
	v_mov_b32_e32 v164, v132
	v_addc_co_u32_e32 v131, vcc, 0, v131, vcc
	global_load_dwordx4 v[148:151], v[130:131], off
	global_load_dwordx4 v[152:155], v[130:131], off offset:1024
	global_load_dwordx4 v[156:159], v[130:131], off offset:2048
	global_load_dwordx4 v[160:163], v[130:131], off offset:3072
	v_mov_b32_e32 v165, v134
	v_mov_b32_e32 v134, v133
	v_pk_mul_f32 v[130:131], v[114:115], v[134:135]
	v_pk_mul_f32 v[114:115], v[114:115], v[164:165]
	v_pk_fma_f32 v[130:131], v[98:99], v[164:165], v[130:131] neg_lo:[0,0,1] neg_hi:[0,0,1]
	s_waitcnt vmcnt(6)
	v_mov_b32_e32 v166, v136
	v_mov_b32_e32 v167, v138
	v_pk_fma_f32 v[98:99], v[98:99], v[134:135], v[114:115]
	v_mov_b32_e32 v138, v137
	v_cvt_pk_f16_f32 v114, v98, v99
	v_pk_mul_f32 v[98:99], v[116:117], v[166:167]
	s_waitcnt vmcnt(5)
	v_mov_b32_e32 v136, v140
	v_mov_b32_e32 v137, v142
	v_pk_fma_f32 v[98:99], v[100:101], v[138:139], v[98:99]
	v_pk_mul_f32 v[132:133], v[116:117], v[138:139]
	v_mov_b32_e32 v142, v141
	v_cvt_pk_f16_f32 v115, v98, v99
	v_pk_mul_f32 v[98:99], v[118:119], v[136:137]
	v_pk_fma_f32 v[132:133], v[100:101], v[166:167], v[132:133] neg_lo:[0,0,1] neg_hi:[0,0,1]
	s_waitcnt vmcnt(4)
	v_mov_b32_e32 v140, v144
	v_mov_b32_e32 v141, v146
	v_mov_b32_e32 v146, v145
	v_pk_fma_f32 v[98:99], v[102:103], v[142:143], v[98:99]
	v_cvt_pk_f16_f32 v130, v130, v131
	v_cvt_pk_f16_f32 v131, v132, v133
	v_pk_mul_f32 v[132:133], v[118:119], v[142:143]
	v_pk_mul_f32 v[144:145], v[120:121], v[146:147]
	v_cvt_pk_f16_f32 v116, v98, v99
	v_pk_mul_f32 v[98:99], v[120:121], v[140:141]
	v_pk_fma_f32 v[132:133], v[102:103], v[136:137], v[132:133] neg_lo:[0,0,1] neg_hi:[0,0,1]
	v_pk_fma_f32 v[144:145], v[104:105], v[140:141], v[144:145] neg_lo:[0,0,1] neg_hi:[0,0,1]
	v_pk_fma_f32 v[98:99], v[104:105], v[146:147], v[98:99]
	v_cvt_pk_f16_f32 v132, v132, v133
	v_cvt_pk_f16_f32 v117, v98, v99
	v_cvt_pk_f16_f32 v133, v144, v145
	s_waitcnt vmcnt(3)
	v_mov_b32_e32 v103, v150
	v_mov_b32_e32 v150, v149
	s_waitcnt vmcnt(2)
	v_mov_b32_e32 v105, v154
	v_mov_b32_e32 v154, v153
	v_mov_b32_e32 v102, v148
	v_pk_mul_f32 v[98:99], v[122:123], v[150:151]
	v_mov_b32_e32 v104, v152
	v_pk_mul_f32 v[100:101], v[124:125], v[154:155]
	v_pk_fma_f32 v[98:99], v[106:107], v[102:103], v[98:99] neg_lo:[0,0,1] neg_hi:[0,0,1]
	v_pk_fma_f32 v[100:101], v[108:109], v[104:105], v[100:101] neg_lo:[0,0,1] neg_hi:[0,0,1]
	v_pk_mul_f32 v[102:103], v[122:123], v[102:103]
	v_pk_mul_f32 v[104:105], v[124:125], v[104:105]
	s_waitcnt vmcnt(1)
	v_mov_b32_e32 v118, v156
	v_mov_b32_e32 v119, v158
	s_waitcnt vmcnt(0)
	v_mov_b32_e32 v120, v160
	v_mov_b32_e32 v121, v162
	v_pk_fma_f32 v[102:103], v[106:107], v[150:151], v[102:103]
	v_pk_fma_f32 v[104:105], v[108:109], v[154:155], v[104:105]
	v_mov_b32_e32 v158, v157
	v_mov_b32_e32 v162, v161
	v_cvt_pk_f16_f32 v102, v102, v103
	v_cvt_pk_f16_f32 v103, v104, v105
	v_pk_mul_f32 v[104:105], v[126:127], v[118:119]
	v_pk_mul_f32 v[106:107], v[128:129], v[120:121]
	v_pk_fma_f32 v[104:105], v[110:111], v[158:159], v[104:105]
	v_pk_fma_f32 v[106:107], v[112:113], v[162:163], v[106:107]
	v_cvt_pk_f16_f32 v104, v104, v105
	v_cvt_pk_f16_f32 v105, v106, v107
	v_mov_b32_e32 v106, v179
	v_cvt_pk_f16_f32 v98, v98, v99
	v_ashrrev_i32_e32 v107, 31, v106
	v_cvt_pk_f16_f32 v99, v100, v101
	v_pk_mul_f32 v[100:101], v[126:127], v[158:159]
	v_pk_mul_f32 v[134:135], v[128:129], v[162:163]
	v_lshl_add_u64 v[106:107], v[106:107], 4, s[58:59]
	v_pk_fma_f32 v[100:101], v[110:111], v[118:119], v[100:101] neg_lo:[0,0,1] neg_hi:[0,0,1]
	v_pk_fma_f32 v[134:135], v[112:113], v[120:121], v[134:135] neg_lo:[0,0,1] neg_hi:[0,0,1]
	global_load_dwordx4 v[108:111], v[106:107], off
	global_load_dwordx4 v[118:121], v[106:107], off offset:1024
	global_load_dwordx4 v[122:125], v[106:107], off offset:2048
	global_load_dwordx4 v[126:129], v[106:107], off offset:3072
	v_add_co_u32_e32 v106, vcc, s47, v106
	v_cvt_pk_f16_f32 v100, v100, v101
	s_nop 0
	v_addc_co_u32_e32 v107, vcc, 0, v107, vcc
	v_cvt_pk_f16_f32 v101, v134, v135
	global_load_dwordx4 v[134:137], v[106:107], off
	global_load_dwordx4 v[138:141], v[106:107], off offset:1024
	global_load_dwordx4 v[142:145], v[106:107], off offset:2048
	global_load_dwordx4 v[146:149], v[106:107], off offset:3072
	s_waitcnt vmcnt(7)
	v_mov_b32_e32 v112, v108
	v_mov_b32_e32 v113, v110
	v_mov_b32_e32 v110, v109
	v_pk_mul_f32 v[106:107], v[82:83], v[110:111]
	v_pk_mul_f32 v[82:83], v[82:83], v[112:113]
	v_pk_fma_f32 v[106:107], v[66:67], v[112:113], v[106:107] neg_lo:[0,0,1] neg_hi:[0,0,1]
	s_waitcnt vmcnt(6)
	v_mov_b32_e32 v150, v118
	v_mov_b32_e32 v151, v120
	v_pk_fma_f32 v[66:67], v[66:67], v[110:111], v[82:83]
	v_mov_b32_e32 v120, v119
	v_cvt_pk_f16_f32 v82, v66, v67
	v_pk_mul_f32 v[66:67], v[84:85], v[150:151]
	s_waitcnt vmcnt(5)
	v_mov_b32_e32 v118, v122
	v_mov_b32_e32 v119, v124
	v_pk_fma_f32 v[66:67], v[68:69], v[120:121], v[66:67]
	v_pk_mul_f32 v[108:109], v[84:85], v[120:121]
	v_mov_b32_e32 v124, v123
	v_cvt_pk_f16_f32 v83, v66, v67
	v_pk_mul_f32 v[66:67], v[86:87], v[118:119]
	v_pk_fma_f32 v[108:109], v[68:69], v[150:151], v[108:109] neg_lo:[0,0,1] neg_hi:[0,0,1]
	s_waitcnt vmcnt(4)
; #define LAS __attribute__((address_space(3)))
; __device__ void fft_phase(const Args& a, LAS unsigned char* lds) {
;     ...
;             for (int p = 0; p < 8; ++p) { const f32x4 cs = tw[p * 64];
;                 tr[2 * p] = Yr[kt][2 * p] * cs[0] - Yi[kt][2 * p] * cs[1]; ti[2 * p] = Yr[kt][2 * p] * cs[1] + Yi[kt][2 * p] * cs[0];
;                 tr[2 * p + 1] = Yr[kt][2 * p + 1] * cs[2] - Yi[kt][2 * p + 1] * cs[3]; ti[2 * p + 1] = Yr[kt][2 * p + 1] * cs[3] + Yi[kt][2 * p + 1] * cs[2]; }
; #pragma unroll
;             for (int sp = 0; sp < 2; ++sp) { trf[kt][sp] = pack_p(tr, sp); tif[kt][sp] = pack_p(ti, sp); }
;         }
; #pragma unroll
;         for (int sp = 0; sp < 2; ++sp)
; #pragma unroll
;             for (int mt2 = 0; mt2 < 2; ++mt2) {
;                 const f16x8 cf = CF[((2 * mt + sp) * 2 + mt2) * 64], nsf = NSF[((2 * mt + sp) * 2 + mt2) * 64];
; #pragma unroll
;                 for (int kt = 0; kt < 2; ++kt) {
;                     X[mt2][kt] = __builtin_amdgcn_mfma_f32_32x32x16_f16(cf, trf[kt][sp], X[mt2][kt], 0, 0, 0);
;                     X[mt2][kt] = __builtin_amdgcn_mfma_f32_32x32x16_f16(nsf, tif[kt][sp], X[mt2][kt], 0, 0, 0);
;                 }
;             }
;     }
; #pragma unroll
;     for (int mt2 = 0; mt2 < 2; ++mt2)
; #pragma unroll
;         for (int kt = 0; kt < 2; ++kt)
; #pragma unroll
;             for (int q = 0; q < 4; ++q) {
;                 const int k1 = 32 * kt + r, c = 8 * mt2 + 2 * q + h;
;                 f16x4 w4;
; #pragma unroll
;                 for (int e = 0; e < 4; ++e) w4[e] = (f16)X[mt2][kt][4 * q + e];
;                 *(LAS f16x4*)(img + k1 * 128 + ((c ^ (k1 & 15)) << 3)) = w4;
;             }
	v_mov_b32_e32 v122, v126
	v_mov_b32_e32 v123, v128
	v_mov_b32_e32 v128, v127
	v_pk_fma_f32 v[66:67], v[70:71], v[124:125], v[66:67]
	v_cvt_pk_f16_f32 v106, v106, v107
	v_cvt_pk_f16_f32 v107, v108, v109
	v_pk_mul_f32 v[108:109], v[86:87], v[124:125]
	v_pk_mul_f32 v[126:127], v[88:89], v[128:129]
	v_cvt_pk_f16_f32 v84, v66, v67
	v_pk_mul_f32 v[66:67], v[88:89], v[122:123]
	v_pk_fma_f32 v[108:109], v[70:71], v[118:119], v[108:109] neg_lo:[0,0,1] neg_hi:[0,0,1]
	v_pk_fma_f32 v[126:127], v[72:73], v[122:123], v[126:127] neg_lo:[0,0,1] neg_hi:[0,0,1]
	v_pk_fma_f32 v[66:67], v[72:73], v[128:129], v[66:67]
	s_waitcnt vmcnt(3)
	v_mov_b32_e32 v71, v136
	v_mov_b32_e32 v136, v135
	s_waitcnt vmcnt(2)
	v_mov_b32_e32 v73, v140
	v_mov_b32_e32 v140, v139
	v_cvt_pk_f16_f32 v85, v66, v67
	v_mov_b32_e32 v70, v134
	v_pk_mul_f32 v[66:67], v[90:91], v[136:137]
	v_mov_b32_e32 v72, v138
	v_pk_mul_f32 v[68:69], v[92:93], v[140:141]
	v_pk_fma_f32 v[66:67], v[74:75], v[70:71], v[66:67] neg_lo:[0,0,1] neg_hi:[0,0,1]
	v_pk_fma_f32 v[68:69], v[76:77], v[72:73], v[68:69] neg_lo:[0,0,1] neg_hi:[0,0,1]
	v_pk_mul_f32 v[70:71], v[90:91], v[70:71]
	v_pk_mul_f32 v[72:73], v[92:93], v[72:73]
	s_waitcnt vmcnt(1)
	v_mov_b32_e32 v86, v142
	v_mov_b32_e32 v87, v144
	s_waitcnt vmcnt(0)
	v_mov_b32_e32 v88, v146
	v_mov_b32_e32 v89, v148
	v_pk_fma_f32 v[70:71], v[74:75], v[136:137], v[70:71]
	v_pk_fma_f32 v[72:73], v[76:77], v[140:141], v[72:73]
	v_mov_b32_e32 v144, v143
	v_mov_b32_e32 v148, v147
	v_cvt_pk_f16_f32 v70, v70, v71
	v_cvt_pk_f16_f32 v71, v72, v73
	v_pk_mul_f32 v[72:73], v[94:95], v[86:87]
	v_pk_mul_f32 v[74:75], v[96:97], v[88:89]
	v_cvt_pk_f16_f32 v66, v66, v67
	v_cvt_pk_f16_f32 v67, v68, v69
	v_pk_mul_f32 v[68:69], v[94:95], v[144:145]
	v_pk_mul_f32 v[110:111], v[96:97], v[148:149]
	v_pk_fma_f32 v[72:73], v[78:79], v[144:145], v[72:73]
	v_pk_fma_f32 v[74:75], v[80:81], v[148:149], v[74:75]
	v_pk_fma_f32 v[68:69], v[78:79], v[86:87], v[68:69] neg_lo:[0,0,1] neg_hi:[0,0,1]
	v_pk_fma_f32 v[110:111], v[80:81], v[88:89], v[110:111] neg_lo:[0,0,1] neg_hi:[0,0,1]
	v_cvt_pk_f16_f32 v72, v72, v73
	v_cvt_pk_f16_f32 v73, v74, v75
	ds_read_b128 v[74:77], v180 offset:4096
	ds_read_b128 v[78:81], v180 offset:20480
	v_cvt_pk_f16_f32 v108, v108, v109
	v_cvt_pk_f16_f32 v109, v126, v127
	s_waitcnt lgkmcnt(1)
	v_mfma_f32_32x32x16_f16 v[18:33], v[74:77], v[130:133], v[18:33]
	v_cvt_pk_f16_f32 v68, v68, v69
	v_cvt_pk_f16_f32 v69, v110, v111
	v_mfma_f32_32x32x16_f16 v[2:17], v[74:77], v[106:109], v[2:17]
	s_waitcnt lgkmcnt(0)
	v_mfma_f32_32x32x16_f16 v[18:33], v[78:81], v[114:117], v[18:33]
	v_mfma_f32_32x32x16_f16 v[2:17], v[78:81], v[82:85], v[2:17]
	ds_read_b128 v[74:77], v180 offset:5120
	ds_read_b128 v[78:81], v180 offset:21504
	s_waitcnt lgkmcnt(1)
	v_mfma_f32_32x32x16_f16 v[50:65], v[74:77], v[130:133], v[50:65]
	v_mfma_f32_32x32x16_f16 v[34:49], v[74:77], v[106:109], v[34:49]
	s_waitcnt lgkmcnt(0)
	v_mfma_f32_32x32x16_f16 v[50:65], v[78:81], v[114:117], v[50:65]
	v_mfma_f32_32x32x16_f16 v[34:49], v[78:81], v[82:85], v[34:49]
	ds_read_b128 v[74:77], v180 offset:6144
	ds_read_b128 v[78:81], v180 offset:22528
	s_waitcnt lgkmcnt(1)
	v_mfma_f32_32x32x16_f16 v[18:33], v[74:77], v[98:101], v[18:33]
	v_mfma_f32_32x32x16_f16 v[2:17], v[74:77], v[66:69], v[2:17]
	s_waitcnt lgkmcnt(0)
	v_mfma_f32_32x32x16_f16 v[18:33], v[78:81], v[102:105], v[18:33]
	v_mfma_f32_32x32x16_f16 v[2:17], v[78:81], v[70:73], v[2:17]
	ds_read_b128 v[74:77], v180 offset:7168
	ds_read_b128 v[78:81], v180 offset:23552
	s_nop 8
	v_cvt_pk_f16_f32 v21, v20, v21
	v_cvt_pk_f16_f32 v20, v18, v19
	v_cvt_pk_f16_f32 v19, v24, v25
	v_cvt_pk_f16_f32 v18, v22, v23
	v_cvt_pk_f16_f32 v23, v28, v29
	v_cvt_pk_f16_f32 v22, v26, v27
	s_waitcnt lgkmcnt(1)
	v_mfma_f32_32x32x16_f16 v[50:65], v[74:77], v[98:101], v[50:65]
	v_cvt_pk_f16_f32 v5, v4, v5
	v_cvt_pk_f16_f32 v4, v2, v3
	v_cvt_pk_f16_f32 v3, v8, v9
	v_cvt_pk_f16_f32 v2, v6, v7
	ds_write2st64_b64 v188, v[18:19], v[2:3] offset1:8
	v_cvt_pk_f16_f32 v3, v12, v13
	v_cvt_pk_f16_f32 v2, v10, v11
	v_mfma_f32_32x32x16_f16 v[34:49], v[74:77], v[66:69], v[34:49]
	v_cvt_pk_f16_f32 v25, v32, v33
	v_cvt_pk_f16_f32 v24, v30, v31
	ds_write2st64_b64 v189, v[22:23], v[2:3] offset1:8
	v_cvt_pk_f16_f32 v3, v16, v17
	v_cvt_pk_f16_f32 v2, v14, v15
	ds_write2st64_b64 v190, v[24:25], v[2:3] offset1:8
	ds_write2st64_b64 v187, v[20:21], v[4:5] offset1:8
	s_waitcnt lgkmcnt(4)
; #define LAS __attribute__((address_space(3)))
; __device__ void fft_phase(const Args& a, LAS unsigned char* lds) {
;     ...
;             }
;     f16x8 gt[8];
;     int tl = tid; asm volatile("" : "+v"(tl));
;     const int tok0 = (tl & 63) + 512 * wid;
; #pragma unroll
;     for (int i = 0; i < 8; ++i) gt[i] = *(const f16x8*)(GF + (blk0 + tok0 + 64 * i) * 8);
;     { const int un = (unit + G < 768) ? unit + G : unit; FFT_LOAD(un); }
;     __syncthreads();
;     {
;         const int k1 = tl & 63;
;         f16x4 vv[8][2];
; #pragma unroll
;         for (int ch = 0; ch < 8; ++ch)
; #pragma unroll
;             for (int cc = 0; cc < 2; ++cc) vv[ch][cc] = *(const LAS f16x4*)(lds + ch * 16384 + k1 * 128 + (((2 * wid + cc) ^ (k1 & 15)) << 3));
; #pragma unroll
	v_mfma_f32_32x32x16_f16 v[50:65], v[78:81], v[102:105], v[50:65]
	v_mov_b32_e32 v102, v178
	v_mfma_f32_32x32x16_f16 v[34:49], v[78:81], v[70:73], v[34:49]
	s_nop 9
	v_cvt_pk_f16_f32 v3, v52, v53
	v_cvt_pk_f16_f32 v2, v50, v51
	v_cvt_pk_f16_f32 v5, v56, v57
	v_cvt_pk_f16_f32 v4, v54, v55
	v_cvt_pk_f16_f32 v7, v60, v61
	v_cvt_pk_f16_f32 v6, v58, v59
	v_cvt_pk_f16_f32 v9, v64, v65
	v_cvt_pk_f16_f32 v11, v36, v37
	v_cvt_pk_f16_f32 v10, v34, v35
	ds_write2st64_b64 v191, v[2:3], v[10:11] offset1:8
	v_cvt_pk_f16_f32 v3, v40, v41
	v_cvt_pk_f16_f32 v2, v38, v39
	ds_write2st64_b64 v192, v[4:5], v[2:3] offset1:8
	v_cvt_pk_f16_f32 v3, v44, v45
	v_cvt_pk_f16_f32 v2, v42, v43
	v_cvt_pk_f16_f32 v8, v62, v63
	ds_write2st64_b64 v193, v[6:7], v[2:3] offset1:8
	v_cvt_pk_f16_f32 v3, v48, v49
	v_cvt_pk_f16_f32 v2, v46, v47
	ds_write2st64_b64 v194, v[8:9], v[2:3] offset1:8
	s_nop 0
	v_and_b32_e32 v98, 63, v102
	v_or_b32_e32 v2, s8, v98
	v_ashrrev_i32_e32 v3, 31, v2
	v_lshl_add_u64 v[114:115], v[2:3], 4, s[66:67]
	v_add_co_u32_e32 v2, vcc, s1, v114
	s_mov_b32 s1, 0xf1002000
	s_nop 0
	v_addc_co_u32_e32 v3, vcc, -1, v115, vcc
	global_load_dwordx4 v[66:69], v[2:3], off offset:-4096
	global_load_dwordx4 v[70:73], v[2:3], off offset:-3072
	global_load_dwordx4 v[74:77], v[2:3], off offset:-2048
	global_load_dwordx4 v[78:81], v[2:3], off offset:-1024
	global_load_dwordx4 v[82:85], v[2:3], off
	v_add_co_u32_e32 v2, vcc, s1, v114
	v_lshl_add_u32 v128, v98, 7, 0
	s_nop 0
	v_addc_co_u32_e32 v3, vcc, -1, v115, vcc
	s_and_b64 vcc, s[6:7], exec
	s_cselect_b32 s6, s5, s0
	s_ashr_i32 s0, s6, 4
	s_and_b32 s0, s0, -4
	s_bfe_u32 s1, s6, 0x20004
	global_load_dwordx4 v[86:89], v[2:3], off offset:-3072
	global_load_dwordx4 v[90:93], v[2:3], off offset:-2048
	global_load_dwordx4 v[94:97], v[2:3], off offset:-1024
	s_or_b32 s0, s0, s1
	v_mov_b32_e32 v2, v178
	s_ashr_i32 s1, s0, 31
	s_lshl_b32 s6, s6, 12
	s_lshl_b64 s[0:1], s[0:1], 16
	s_and_b32 s6, s6, 0xf000
	v_lshlrev_b32_e32 v2, 1, v2
	s_or_b32 s0, s0, s6
	v_ashrrev_i32_e32 v3, 31, v2
	v_lshl_add_u64 v[4:5], s[0:1], 1, v[2:3]
	v_lshlrev_b64 v[4:5], 4, v[4:5]
	v_lshl_add_u64 v[4:5], s[16:17], 0, v[4:5]
	s_mov_b64 s[100:101], 0x10000
	global_load_dwordx4 v[58:61], v[4:5], off
	global_load_dwordx4 v[62:65], v[4:5], off offset:16
	v_lshl_add_u64 v[50:51], v[4:5], 0, s[100:101]
	global_load_dwordx4 v[54:57], v[50:51], off offset:16
	s_nop 0
	global_load_dwordx4 v[50:53], v[50:51], off
	v_add_u32_e32 v4, 0x400, v2
	v_ashrrev_i32_e32 v5, 31, v4
	v_lshl_add_u64 v[4:5], s[0:1], 1, v[4:5]
	v_lshlrev_b64 v[4:5], 4, v[4:5]
	v_lshl_add_u64 v[4:5], s[16:17], 0, v[4:5]
	global_load_dwordx4 v[42:45], v[4:5], off
	global_load_dwordx4 v[46:49], v[4:5], off offset:16
	v_lshl_add_u64 v[34:35], v[4:5], 0, s[100:101]
	global_load_dwordx4 v[38:41], v[34:35], off offset:16
	s_nop 0
	global_load_dwordx4 v[34:37], v[34:35], off
	v_add_u32_e32 v4, 0x800, v2
	v_add_u32_e32 v2, 0xc00, v2
	v_ashrrev_i32_e32 v5, 31, v4
	v_ashrrev_i32_e32 v3, 31, v2
	v_lshl_add_u64 v[4:5], s[0:1], 1, v[4:5]
	v_lshl_add_u64 v[2:3], s[0:1], 1, v[2:3]
	v_lshlrev_b64 v[4:5], 4, v[4:5]
	v_lshlrev_b64 v[2:3], 4, v[2:3]
	v_lshl_add_u64 v[4:5], s[16:17], 0, v[4:5]
	v_lshl_add_u64 v[6:7], s[16:17], 0, v[2:3]
	global_load_dwordx4 v[26:29], v[4:5], off
	global_load_dwordx4 v[30:33], v[4:5], off offset:16
	v_lshl_add_u64 v[18:19], v[4:5], 0, s[100:101]
	global_load_dwordx4 v[22:25], v[18:19], off offset:16
	s_nop 0
	global_load_dwordx4 v[18:21], v[18:19], off
	global_load_dwordx4 v[10:13], v[6:7], off
	global_load_dwordx4 v[14:17], v[6:7], off offset:16
	v_lshl_add_u64 v[2:3], v[6:7], 0, s[100:101]
	global_load_dwordx4 v[6:9], v[2:3], off offset:16
	s_nop 0
	global_load_dwordx4 v[2:5], v[2:3], off
	v_bitop3_b32 v98, v102, s9, 15 bitop3:0x6c
	v_bitop3_b32 v102, v102, s12, 15 bitop3:0x6c
	v_lshlrev_b32_e32 v129, 3, v98
	v_lshlrev_b32_e32 v130, 3, v102
	v_add_u32_e32 v118, 0x10000, v128
	v_add_u32_e32 v122, 0x14000, v128
	v_add_u32_e32 v126, 0x18000, v128
	v_add_u32_e32 v131, 0x1c000, v128
	v_add_u32_e32 v106, v128, v129
	v_add_u32_e32 v110, v128, v130
	v_add_u32_e32 v116, v118, v129
	v_add_u32_e32 v118, v118, v130
	v_add_u32_e32 v120, v122, v129
	v_add_u32_e32 v124, v126, v129
	v_add_u32_e32 v126, v126, v130
	v_add_u32_e32 v128, v131, v129
	s_waitcnt lgkmcnt(0)
	s_barrier
; #define LAS __attribute__((address_space(3)))
; __device__ void fft_phase(const Args& a, LAS unsigned char* lds) {
;     ...
;     {
;         const int k1 = tl & 63;
;         f16x4 vv[8][2];
; #pragma unroll
;         for (int ch = 0; ch < 8; ++ch)
; #pragma unroll
;             for (int cc = 0; cc < 2; ++cc) vv[ch][cc] = *(const LAS f16x4*)(lds + ch * 16384 + k1 * 128 + (((2 * wid + cc) ^ (k1 & 15)) << 3));
; #pragma unroll
;         for (int i = 0; i < 8; ++i) {
;             f16x8 o;
; #pragma unroll
;             for (int ch = 0; ch < 8; ++ch) o[ch] = vv[ch][i >> 2][i & 3];
;             o = o * gt[i];
;             *(f16x8*)(FOUR + (blk0 + tok0 + 64 * i) * 8) = o;
;         }
;     }
	ds_read2st64_b64 v[98:101], v106 offset1:32
	ds_read2st64_b64 v[102:105], v110 offset1:32
	ds_read2st64_b64 v[106:109], v106 offset0:64 offset1:96
	ds_read2st64_b64 v[110:113], v110 offset0:64 offset1:96
	ds_read_b64 v[116:117], v116
	ds_read_b64 v[118:119], v118
	ds_read_b64 v[120:121], v120
	ds_read_b64 v[124:125], v124
	ds_read_b64 v[126:127], v126
	ds_read_b64 v[128:129], v128
	v_add_u32_e32 v122, v122, v130
	v_add_u32_e32 v130, v131, v130
	ds_read_b64 v[122:123], v122
	ds_read_b64 v[130:131], v130
	s_waitcnt lgkmcnt(11)
	v_perm_b32 v132, v100, v98, s48
	s_waitcnt lgkmcnt(9)
	v_perm_b32 v133, v108, v106, s48
	s_waitcnt lgkmcnt(5)
	v_perm_b32 v134, v120, v116, s48
	s_waitcnt lgkmcnt(2)
	v_perm_b32 v135, v128, v124, s48
	s_waitcnt vmcnt(23)
	v_pk_mul_f16 v69, v69, v135
	v_pk_mul_f16 v68, v68, v134
	v_pk_mul_f16 v67, v67, v133
	v_pk_mul_f16 v66, v66, v132
	global_store_dwordx4 v[114:115], v[66:69], off
	s_add_u32 s66, s66, s34
	s_addc_u32 s67, s67, s35
	v_perm_b32 v66, v100, v98, s49
	v_perm_b32 v67, v108, v106, s49
	v_perm_b32 v68, v120, v116, s49
	v_perm_b32 v69, v128, v124, s49
	s_waitcnt vmcnt(23)
	v_pk_mul_f16 v69, v73, v69
	v_pk_mul_f16 v68, v72, v68
	v_pk_mul_f16 v67, v71, v67
	v_pk_mul_f16 v66, v70, v66
	global_store_dwordx4 v[114:115], v[66:69], off offset:1024
	v_add_co_u32_e64 v70, s[0:1], s47, v114
	s_nop 0
	v_perm_b32 v66, v101, v99, s48
	v_perm_b32 v67, v109, v107, s48
	v_perm_b32 v68, v121, v117, s48
	v_perm_b32 v69, v129, v125, s48
	s_waitcnt vmcnt(23)
	v_pk_mul_f16 v69, v77, v69
	v_pk_mul_f16 v68, v76, v68
	v_pk_mul_f16 v67, v75, v67
	v_pk_mul_f16 v66, v74, v66
	global_store_dwordx4 v[114:115], v[66:69], off offset:2048
	v_addc_co_u32_e64 v71, s[0:1], 0, v115, s[0:1]
	s_nop 0
	v_perm_b32 v66, v101, v99, s49
	v_perm_b32 v67, v109, v107, s49
	v_perm_b32 v68, v121, v117, s49
	v_perm_b32 v69, v129, v125, s49
	s_waitcnt vmcnt(23)
	v_pk_mul_f16 v69, v81, v69
	v_pk_mul_f16 v68, v80, v68
	v_pk_mul_f16 v67, v79, v67
	v_pk_mul_f16 v66, v78, v66
	global_store_dwordx4 v[114:115], v[66:69], off offset:3072
	s_mov_b32 s0, s5
	s_nop 0
	v_perm_b32 v66, v104, v102, s48
	v_perm_b32 v67, v112, v110, s48
	s_waitcnt lgkmcnt(1)
	v_perm_b32 v68, v122, v118, s48
	s_waitcnt lgkmcnt(0)
	v_perm_b32 v69, v130, v126, s48
	s_waitcnt vmcnt(23)
	v_pk_mul_f16 v69, v85, v69
	v_pk_mul_f16 v68, v84, v68
	v_pk_mul_f16 v67, v83, v67
	v_pk_mul_f16 v66, v82, v66
	global_store_dwordx4 v[70:71], v[66:69], off
	s_nop 1
	v_perm_b32 v66, v104, v102, s49
	v_perm_b32 v67, v112, v110, s49
	v_perm_b32 v68, v122, v118, s49
	v_perm_b32 v69, v130, v126, s49
	s_waitcnt vmcnt(23)
	v_pk_mul_f16 v69, v89, v69
	v_pk_mul_f16 v68, v88, v68
	v_pk_mul_f16 v67, v87, v67
	v_pk_mul_f16 v66, v86, v66
	global_store_dwordx4 v[70:71], v[66:69], off offset:1024
	s_nop 1
	v_perm_b32 v66, v105, v103, s48
	v_perm_b32 v67, v113, v111, s48
	v_perm_b32 v68, v123, v119, s48
	v_perm_b32 v69, v131, v127, s48
	s_waitcnt vmcnt(23)
	v_pk_mul_f16 v69, v93, v69
	v_pk_mul_f16 v68, v92, v68
	v_pk_mul_f16 v67, v91, v67
	v_pk_mul_f16 v66, v90, v66
	global_store_dwordx4 v[70:71], v[66:69], off offset:2048
	s_nop 1
	v_perm_b32 v66, v105, v103, s49
	v_perm_b32 v67, v113, v111, s49
	v_perm_b32 v68, v123, v119, s49
	v_perm_b32 v69, v131, v127, s49
	s_waitcnt vmcnt(23)
	v_pk_mul_f16 v69, v97, v69
	v_pk_mul_f16 v68, v96, v68
	v_pk_mul_f16 v67, v95, v67
	v_pk_mul_f16 v66, v94, v66
	global_store_dwordx4 v[70:71], v[66:69], off offset:3072
	s_cbranch_vccnz .LBB0_392
